# tconv all six: two pairs of loads in flight (two register sets), LDS double buffer, one barrier per pair
# baseline (speedup 1.0000x reference)
; __device__ __forceinline__ u32x4 pack8(const float* f) { u32x4 w; w.x = pk2(f[0], f[1]); w.y = pk2(f[2], f[3]); w.z = pk2(f[4], f[5]); w.w = pk2(f[6], f[7]); return w; }
; __device__ void tconv(unsigned char* smem, const float* src, int ldsrc, int col0, int N, int K, u16* dst, int ldd) {
;     float* T = (float*)smem;
;     const int tid = threadIdx.x, tilesN = N >> 6, ntile = tilesN * (K >> 6);
;     const int lr = tid >> 4, lc = (tid & 15) * 4;
;     const int sn = tid >> 3, sk = (tid & 7) * 8;
;     int tile = blockIdx.x;
;     f32x4 v0 = {0.f, 0.f, 0.f, 0.f}, v1 = {0.f, 0.f, 0.f, 0.f};
;     if (tile < ntile) { const int tn = tile % tilesN, tk = tile / tilesN; const float* s = src + (size_t)(tk * 64 + lr) * ldsrc + col0 + tn * 64 + lc;
;         v0 = __builtin_nontemporal_load((const f32x4*)s); v1 = __builtin_nontemporal_load((const f32x4*)(s + (size_t)32 * ldsrc)); }
;     for (; tile < ntile; tile += gridDim.x) {
;         const int tn = tile % tilesN, tk = tile / tilesN;
; #pragma unroll
;         for (int j = 0; j < 4; ++j) { T[lr * 65 + lc + j] = v0[j]; T[(lr + 32) * 65 + lc + j] = v1[j]; }
;         asm volatile("s_waitcnt lgkmcnt(0)" ::: "memory"); __builtin_amdgcn_s_barrier(); asm volatile("" ::: "memory");
;         const int nx = tile + gridDim.x;
;         if (nx < ntile) { const int tn2 = nx % tilesN, tk2 = nx / tilesN; const float* s = src + (size_t)(tk2 * 64 + lr) * ldsrc + col0 + tn2 * 64 + lc;
;             v0 = __builtin_nontemporal_load((const f32x4*)s); v1 = __builtin_nontemporal_load((const f32x4*)(s + (size_t)32 * ldsrc)); }
;         float f[8];
; #pragma unroll
;         for (int j = 0; j < 8; ++j) f[j] = T[(sk + j) * 65 + sn];
;         *(u32x4*)(dst + (size_t)(tn * 64 + sn) * ldd + tk * 64 + sk) = pack8(f);
;         asm volatile("s_waitcnt lgkmcnt(0)" ::: "memory"); __builtin_amdgcn_s_barrier(); asm volatile("" ::: "memory");
;     }
;     __syncthreads();
; }
_Z4mega6Params:
	s_mov_b32 s100, 0
	s_mov_b32 s70, s2
	s_mov_b64 s[16:17], s[0:1]
	s_load_dwordx2 s[88:89], s[0:1], 0x0
	s_nop 0
	s_load_dwordx16 s[0:15], s[16:17], 0x10
	s_add_u32 s68, s16, 0x160
	s_addc_u32 s69, s17, 0
	s_waitcnt lgkmcnt(0)
	v_writelane_b32 v251, s0, 0
	s_nop 1
	v_writelane_b32 v251, s1, 1
	v_writelane_b32 v251, s2, 2
	v_writelane_b32 v251, s3, 3
	v_writelane_b32 v251, s4, 4
	v_writelane_b32 v251, s5, 5
	v_writelane_b32 v251, s6, 6
	v_writelane_b32 v251, s7, 7
	v_writelane_b32 v251, s8, 8
	v_writelane_b32 v251, s9, 9
	v_writelane_b32 v251, s10, 10
	v_writelane_b32 v251, s11, 11
	v_writelane_b32 v251, s12, 12
	v_writelane_b32 v251, s13, 13
	v_writelane_b32 v251, s14, 14
	v_writelane_b32 v251, s15, 15
	s_load_dwordx16 s[72:87], s[16:17], 0x50
	s_load_dwordx4 s[64:67], s[16:17], 0x150
	s_load_dwordx16 s[0:15], s[16:17], 0x90
	s_waitcnt lgkmcnt(0)
	s_cmp_lt_i32 s66, 1
	v_writelane_b32 v251, s0, 16
	s_nop 1
	v_writelane_b32 v251, s1, 17
	v_writelane_b32 v251, s2, 18
	v_writelane_b32 v251, s3, 19
	v_writelane_b32 v251, s4, 20
	v_writelane_b32 v251, s5, 21
	v_writelane_b32 v251, s6, 22
	v_writelane_b32 v251, s7, 23
	v_writelane_b32 v251, s8, 24
	v_writelane_b32 v251, s9, 25
	v_writelane_b32 v251, s10, 26
	v_writelane_b32 v251, s11, 27
	v_writelane_b32 v251, s12, 28
	v_writelane_b32 v251, s13, 29
	v_writelane_b32 v251, s14, 30
	v_writelane_b32 v251, s15, 31
	v_writelane_b32 v251, s16, 32
	s_load_dword s62, s[16:17], 0x160
	s_cselect_b64 s[0:1], -1, 0
	s_cmp_gt_i32 s67, 0
	s_cselect_b64 s[2:3], -1, 0
	s_and_b64 s[0:1], s[0:1], s[2:3]
	s_andn2_b64 vcc, exec, s[0:1]
	v_writelane_b32 v251, s17, 33
	s_cbranch_vccnz .LBB0_25
	v_and_b32_e32 v1, 0x3ff, v0
	v_lshlrev_b32_e32 v14, 2, v1
	v_bfe_u32 v16, v0, 4, 6
	v_and_b32_e32 v2, 60, v14
	v_lshlrev_b32_e32 v15, 3, v1
	v_lshlrev_b32_e32 v10, 2, v2
	v_mul_u32_u24_e32 v2, 0x41, v16
	v_bfe_u32 v17, v0, 3, 7
	v_and_b32_e32 v19, 56, v15
	v_lshlrev_b32_e32 v2, 2, v2
	s_cmpk_gt_i32 s70, 0xfff
	v_mov_b32_e32 v11, 0
	v_add3_u32 v18, 0, v10, v2
	v_add3_u32 v20, 0, v2, v10
	v_lshl_add_u32 v21, v17, 2, 0
	v_mul_u32_u24_e32 v22, 0x104, v19
	s_cbranch_scc1 .LBB0_8
	s_waitcnt vmcnt(0) lgkmcnt(0)
	s_barrier
	v_readlane_b32 s56, v251, 32
	v_readlane_b32 s57, v251, 33
	v_and_b32_e32 v142, 0x3ff, v0
	v_lshrrev_b32_e32 v153, 4, v142
	v_and_b32_e32 v154, 15, v142
	v_lshlrev_b32_e32 v154, 4, v154
	v_lshlrev_b32_e32 v143, 15, v153
	s_load_dwordx2 s[40:41], s[56:57], 0x10
	v_add_u32_e32 v143, v143, v154
	v_mul_u32_u24_e32 v145, 0x104, v153
	v_add_u32_e32 v145, v145, v154
	v_add_u32_e32 v146, 0x2080, v145
	v_add_u32_e32 v147, 0x4100, v145
	v_add_u32_e32 v148, 0x6180, v145
	v_lshrrev_b32_e32 v153, 3, v142
	v_and_b32_e32 v154, 7, v142
	v_mul_u32_u24_e32 v149, 0x820, v154
	v_lshl_add_u32 v149, v153, 2, v149
	v_add_u32_e32 v150, 0x400, v149
	v_add_u32_e32 v151, 0x4100, v149
	v_add_u32_e32 v152, 0x4500, v149
	v_add_u32_e32 v173, 0x8200, v145
	v_add_u32_e32 v174, 0x8200, v146
	v_add_u32_e32 v175, 0x8200, v147
	v_add_u32_e32 v176, 0x8200, v148
	v_add_u32_e32 v177, 0x8200, v149
	v_add_u32_e32 v178, 0x8200, v150
	v_add_u32_e32 v120, 0x8200, v151
	v_add_u32_e32 v121, 0x8200, v152
	v_lshlrev_b32_e32 v144, 12, v153
	v_lshl_add_u32 v144, v154, 4, v144
	s_add_u32 s44, s64, 0x1c000000
	s_addc_u32 s45, s65, 0
	s_lshl_b32 s54, s62, 1
	s_mov_b32 s46, s70
	s_waitcnt lgkmcnt(0)
	s_add_u32 s42, s40, 0x100000
	s_addc_u32 s43, s41, 0
	s_add_i32 s47, s46, s62
	s_cmpk_lt_i32 s47, 0x1000
	s_cselect_b32 s47, s47, s46
	s_and_b32 s52, s46, 0x7f
	s_lshr_b32 s53, s46, 7
	s_lshl_b32 s52, s52, 8
	s_lshl_b32 s53, s53, 21
	s_add_i32 s48, s52, s53
	s_and_b32 s52, s47, 0x7f
	s_lshr_b32 s53, s47, 7
	s_lshl_b32 s52, s52, 8
	s_lshl_b32 s53, s53, 21
	s_add_i32 s49, s52, s53
	v_add_u32_e32 v153, s48, v143
	v_add_u32_e32 v172, s49, v143
	global_load_dwordx4 v[70:73], v153, s[40:41] nt
	global_load_dwordx4 v[74:77], v153, s[42:43] nt
	global_load_dwordx4 v[78:81], v172, s[40:41] nt
	global_load_dwordx4 v[82:85], v172, s[42:43] nt
	s_add_i32 s55, s46, s54
	s_cmpk_lt_i32 s55, 0x1000
	s_cbranch_scc0 TCV1_pro1
	s_add_i32 s47, s55, s62
	s_cmpk_lt_i32 s47, 0x1000
	s_cselect_b32 s47, s47, s55
	s_and_b32 s52, s55, 0x7f
	s_lshr_b32 s53, s55, 7
	s_lshl_b32 s52, s52, 8
	s_lshl_b32 s53, s53, 21
	s_add_i32 s48, s52, s53
	s_and_b32 s52, s47, 0x7f
	s_lshr_b32 s53, s47, 7
	s_lshl_b32 s52, s52, 8
	s_lshl_b32 s53, s53, 21
	s_add_i32 s49, s52, s53
	v_add_u32_e32 v153, s48, v143
	v_add_u32_e32 v172, s49, v143
	global_load_dwordx4 v[104:107], v153, s[40:41] nt
	global_load_dwordx4 v[108:111], v153, s[42:43] nt
	global_load_dwordx4 v[112:115], v172, s[40:41] nt
	global_load_dwordx4 v[116:119], v172, s[42:43] nt
	s_waitcnt vmcnt(4)
	s_branch TCV1_bodyX
TCV1_pro1:
	s_waitcnt vmcnt(0)
TCV1_bodyX:
	ds_write2_b32 v145, v70, v71 offset1:1
	ds_write2_b32 v145, v72, v73 offset0:2 offset1:3
	ds_write2_b32 v146, v74, v75 offset1:1
	ds_write2_b32 v146, v76, v77 offset0:2 offset1:3
	ds_write2_b32 v147, v78, v79 offset1:1
	ds_write2_b32 v147, v80, v81 offset0:2 offset1:3
	ds_write2_b32 v148, v82, v83 offset1:1
	ds_write2_b32 v148, v84, v85 offset0:2 offset1:3
	s_add_i32 s47, s46, s62
	s_cmpk_lt_i32 s47, 0x1000
	s_cselect_b32 s47, s47, s46
	s_and_b32 s52, s46, 0x7f
	s_lshr_b32 s53, s46, 7
	s_lshl_b32 s52, s52, 18
	s_lshl_b32 s53, s53, 7
	s_add_i32 s50, s52, s53
	s_and_b32 s52, s47, 0x7f
	s_lshr_b32 s53, s47, 7
	s_lshl_b32 s52, s52, 18
	s_lshl_b32 s53, s53, 7
	s_add_i32 s51, s52, s53
	s_waitcnt lgkmcnt(0)
	s_barrier
	s_add_i32 s55, s46, s54
	s_add_i32 s55, s55, s54
	s_cmpk_lt_i32 s55, 0x1000
	s_cbranch_scc0 TCV1_noloadX
	s_add_i32 s47, s55, s62
	s_cmpk_lt_i32 s47, 0x1000
	s_cselect_b32 s47, s47, s55
	s_and_b32 s52, s55, 0x7f
	s_lshr_b32 s53, s55, 7
	s_lshl_b32 s52, s52, 8
	s_lshl_b32 s53, s53, 21
	s_add_i32 s48, s52, s53
	s_and_b32 s52, s47, 0x7f
	s_lshr_b32 s53, s47, 7
	s_lshl_b32 s52, s52, 8
	s_lshl_b32 s53, s53, 21
	s_add_i32 s49, s52, s53
	v_add_u32_e32 v153, s48, v143
	v_add_u32_e32 v172, s49, v143
	global_load_dwordx4 v[70:73], v153, s[40:41] nt
	global_load_dwordx4 v[74:77], v153, s[42:43] nt
	global_load_dwordx4 v[78:81], v172, s[40:41] nt
	global_load_dwordx4 v[82:85], v172, s[42:43] nt
; __device__ __forceinline__ u32x4 pack8(const float* f) { u32x4 w; w.x = pk2(f[0], f[1]); w.y = pk2(f[2], f[3]); w.z = pk2(f[4], f[5]); w.w = pk2(f[6], f[7]); return w; }
; __device__ void tconv(unsigned char* smem, const float* src, int ldsrc, int col0, int N, int K, u16* dst, int ldd) {
;     float* T = (float*)smem;
;     const int tid = threadIdx.x, tilesN = N >> 6, ntile = tilesN * (K >> 6);
;     const int lr = tid >> 4, lc = (tid & 15) * 4;
;     const int sn = tid >> 3, sk = (tid & 7) * 8;
;     int tile = blockIdx.x;
;     f32x4 v0 = {0.f, 0.f, 0.f, 0.f}, v1 = {0.f, 0.f, 0.f, 0.f};
;     if (tile < ntile) { const int tn = tile % tilesN, tk = tile / tilesN; const float* s = src + (size_t)(tk * 64 + lr) * ldsrc + col0 + tn * 64 + lc;
;         v0 = __builtin_nontemporal_load((const f32x4*)s); v1 = __builtin_nontemporal_load((const f32x4*)(s + (size_t)32 * ldsrc)); }
;     for (; tile < ntile; tile += gridDim.x) {
;         const int tn = tile % tilesN, tk = tile / tilesN;
; #pragma unroll
;         for (int j = 0; j < 4; ++j) { T[lr * 65 + lc + j] = v0[j]; T[(lr + 32) * 65 + lc + j] = v1[j]; }
;         asm volatile("s_waitcnt lgkmcnt(0)" ::: "memory"); __builtin_amdgcn_s_barrier(); asm volatile("" ::: "memory");
;         const int nx = tile + gridDim.x;
;         if (nx < ntile) { const int tn2 = nx % tilesN, tk2 = nx / tilesN; const float* s = src + (size_t)(tk2 * 64 + lr) * ldsrc + col0 + tn2 * 64 + lc;
;             v0 = __builtin_nontemporal_load((const f32x4*)s); v1 = __builtin_nontemporal_load((const f32x4*)(s + (size_t)32 * ldsrc)); }
;         float f[8];
; #pragma unroll
;         for (int j = 0; j < 8; ++j) f[j] = T[(sk + j) * 65 + sn];
;         *(u32x4*)(dst + (size_t)(tn * 64 + sn) * ldd + tk * 64 + sk) = pack8(f);
;         asm volatile("s_waitcnt lgkmcnt(0)" ::: "memory"); __builtin_amdgcn_s_barrier(); asm volatile("" ::: "memory");
;     }
;     __syncthreads();
; }
TCV1_noloadX:
	ds_read2_b32 v[156:157], v149 offset1:65
	ds_read2_b32 v[158:159], v149 offset0:130 offset1:195
	ds_read2_b32 v[160:161], v150 offset0:4 offset1:69
	ds_read2_b32 v[162:163], v150 offset0:134 offset1:199
	ds_read2_b32 v[164:165], v151 offset1:65
	ds_read2_b32 v[166:167], v151 offset0:130 offset1:195
	ds_read2_b32 v[168:169], v152 offset0:4 offset1:69
	ds_read2_b32 v[170:171], v152 offset0:134 offset1:199
	v_add_u32_e32 v154, s50, v144
	v_add_u32_e32 v155, s51, v144
	s_waitcnt lgkmcnt(7)
	v_cvt_pk_bf16_f32 v156, v156, v157
	s_waitcnt lgkmcnt(6)
	v_cvt_pk_bf16_f32 v157, v158, v159
	s_waitcnt lgkmcnt(5)
	v_cvt_pk_bf16_f32 v158, v160, v161
	s_waitcnt lgkmcnt(4)
	v_cvt_pk_bf16_f32 v159, v162, v163
	global_store_dwordx4 v154, v[156:159], s[44:45]
	s_waitcnt lgkmcnt(3)
	v_cvt_pk_bf16_f32 v164, v164, v165
	s_waitcnt lgkmcnt(2)
	v_cvt_pk_bf16_f32 v165, v166, v167
	s_waitcnt lgkmcnt(1)
	v_cvt_pk_bf16_f32 v166, v168, v169
	s_waitcnt lgkmcnt(0)
	v_cvt_pk_bf16_f32 v167, v170, v171
	global_store_dwordx4 v155, v[164:167], s[44:45]
	s_add_i32 s46, s46, s54
	s_cmpk_lt_i32 s46, 0x1000
	s_cbranch_scc0 TCV1_exit
	s_cmpk_lt_i32 s55, 0x1000
	s_cbranch_scc1 TCV1_w6X
	s_waitcnt vmcnt(2)
TCV1_w6X:
	s_waitcnt vmcnt(6)
TCV1_bodyY:
	ds_write2_b32 v173, v104, v105 offset1:1
	ds_write2_b32 v173, v106, v107 offset0:2 offset1:3
	ds_write2_b32 v174, v108, v109 offset1:1
	ds_write2_b32 v174, v110, v111 offset0:2 offset1:3
	ds_write2_b32 v175, v112, v113 offset1:1
	ds_write2_b32 v175, v114, v115 offset0:2 offset1:3
	ds_write2_b32 v176, v116, v117 offset1:1
	ds_write2_b32 v176, v118, v119 offset0:2 offset1:3
	s_add_i32 s47, s46, s62
	s_cmpk_lt_i32 s47, 0x1000
	s_cselect_b32 s47, s47, s46
	s_and_b32 s52, s46, 0x7f
	s_lshr_b32 s53, s46, 7
	s_lshl_b32 s52, s52, 18
	s_lshl_b32 s53, s53, 7
	s_add_i32 s50, s52, s53
	s_and_b32 s52, s47, 0x7f
	s_lshr_b32 s53, s47, 7
	s_lshl_b32 s52, s52, 18
	s_lshl_b32 s53, s53, 7
	s_add_i32 s51, s52, s53
	s_waitcnt lgkmcnt(0)
	s_barrier
	s_add_i32 s55, s46, s54
	s_add_i32 s55, s55, s54
	s_cmpk_lt_i32 s55, 0x1000
	s_cbranch_scc0 TCV1_noloadY
	s_add_i32 s47, s55, s62
	s_cmpk_lt_i32 s47, 0x1000
	s_cselect_b32 s47, s47, s55
	s_and_b32 s52, s55, 0x7f
	s_lshr_b32 s53, s55, 7
	s_lshl_b32 s52, s52, 8
	s_lshl_b32 s53, s53, 21
	s_add_i32 s48, s52, s53
	s_and_b32 s52, s47, 0x7f
	s_lshr_b32 s53, s47, 7
	s_lshl_b32 s52, s52, 8
	s_lshl_b32 s53, s53, 21
	s_add_i32 s49, s52, s53
	v_add_u32_e32 v153, s48, v143
	v_add_u32_e32 v172, s49, v143
	global_load_dwordx4 v[104:107], v153, s[40:41] nt
	global_load_dwordx4 v[108:111], v153, s[42:43] nt
	global_load_dwordx4 v[112:115], v172, s[40:41] nt
	global_load_dwordx4 v[116:119], v172, s[42:43] nt
TCV1_noloadY:
	ds_read2_b32 v[156:157], v177 offset1:65
	ds_read2_b32 v[158:159], v177 offset0:130 offset1:195
	ds_read2_b32 v[160:161], v178 offset0:4 offset1:69
	ds_read2_b32 v[162:163], v178 offset0:134 offset1:199
	ds_read2_b32 v[164:165], v120 offset1:65
	ds_read2_b32 v[166:167], v120 offset0:130 offset1:195
	ds_read2_b32 v[168:169], v121 offset0:4 offset1:69
	ds_read2_b32 v[170:171], v121 offset0:134 offset1:199
	v_add_u32_e32 v154, s50, v144
	v_add_u32_e32 v155, s51, v144
	s_waitcnt lgkmcnt(7)
	v_cvt_pk_bf16_f32 v156, v156, v157
	s_waitcnt lgkmcnt(6)
	v_cvt_pk_bf16_f32 v157, v158, v159
	s_waitcnt lgkmcnt(5)
	v_cvt_pk_bf16_f32 v158, v160, v161
	s_waitcnt lgkmcnt(4)
	v_cvt_pk_bf16_f32 v159, v162, v163
	global_store_dwordx4 v154, v[156:159], s[44:45]
	s_waitcnt lgkmcnt(3)
	v_cvt_pk_bf16_f32 v164, v164, v165
	s_waitcnt lgkmcnt(2)
	v_cvt_pk_bf16_f32 v165, v166, v167
	s_waitcnt lgkmcnt(1)
	v_cvt_pk_bf16_f32 v166, v168, v169
	s_waitcnt lgkmcnt(0)
	v_cvt_pk_bf16_f32 v167, v170, v171
	global_store_dwordx4 v155, v[164:167], s[44:45]
	s_add_i32 s46, s46, s54
	s_cmpk_lt_i32 s46, 0x1000
	s_cbranch_scc0 TCV1_exit
	s_cmpk_lt_i32 s55, 0x1000
	s_cbranch_scc1 TCV1_w6Y
	s_waitcnt vmcnt(2)
TCV1_w6Y:
	s_waitcnt vmcnt(6)
	s_branch TCV1_bodyX
TCV1_exit:
.LBB0_8:
	s_cmpk_gt_i32 s70, 0x7ff
	s_waitcnt lgkmcnt(0)
	s_barrier
	s_cbranch_scc1 .LBB0_15
	s_waitcnt vmcnt(0) lgkmcnt(0)
	s_barrier
	v_readlane_b32 s56, v251, 32
	v_readlane_b32 s57, v251, 33
	v_and_b32_e32 v142, 0x3ff, v0
	v_lshrrev_b32_e32 v153, 4, v142
	v_and_b32_e32 v154, 15, v142
	v_lshlrev_b32_e32 v154, 4, v154
	v_lshlrev_b32_e32 v143, 13, v153
	s_load_dwordx2 s[40:41], s[56:57], 0xa8
	v_add_u32_e32 v143, v143, v154
	v_mul_u32_u24_e32 v145, 0x104, v153
	v_add_u32_e32 v145, v145, v154
	v_add_u32_e32 v146, 0x2080, v145
	v_add_u32_e32 v147, 0x4100, v145
	v_add_u32_e32 v148, 0x6180, v145
	v_lshrrev_b32_e32 v153, 3, v142
	v_and_b32_e32 v154, 7, v142
	v_mul_u32_u24_e32 v149, 0x820, v154
	v_lshl_add_u32 v149, v153, 2, v149
	v_add_u32_e32 v150, 0x400, v149
	v_add_u32_e32 v151, 0x4100, v149
	v_add_u32_e32 v152, 0x4500, v149
	v_add_u32_e32 v173, 0x8200, v145
	v_add_u32_e32 v174, 0x8200, v146
	v_add_u32_e32 v175, 0x8200, v147
	v_add_u32_e32 v176, 0x8200, v148
	v_add_u32_e32 v177, 0x8200, v149
	v_add_u32_e32 v178, 0x8200, v150
	v_add_u32_e32 v120, 0x8200, v151
	v_add_u32_e32 v121, 0x8200, v152
	v_lshlrev_b32_e32 v144, 13, v153
	v_lshl_add_u32 v144, v154, 4, v144
	s_add_u32 s44, s64, 0x1e000000
	s_addc_u32 s45, s65, 0
	s_lshl_b32 s54, s62, 1
	s_mov_b32 s46, s70
	s_waitcnt lgkmcnt(0)
	s_add_u32 s42, s40, 0x40000
	s_addc_u32 s43, s41, 0
	s_add_i32 s47, s46, s62
	s_cmpk_lt_i32 s47, 0x800
	s_cselect_b32 s47, s47, s46
	s_and_b32 s52, s46, 0x1f
	s_lshr_b32 s53, s46, 5
	s_lshl_b32 s52, s52, 8
	s_lshl_b32 s53, s53, 19
	s_add_i32 s48, s52, s53
	s_and_b32 s52, s47, 0x1f
	s_lshr_b32 s53, s47, 5
	s_lshl_b32 s52, s52, 8
	s_lshl_b32 s53, s53, 19
	s_add_i32 s49, s52, s53
	v_add_u32_e32 v153, s48, v143
	v_add_u32_e32 v172, s49, v143
	global_load_dwordx4 v[70:73], v153, s[40:41] nt
	global_load_dwordx4 v[74:77], v153, s[42:43] nt
	global_load_dwordx4 v[78:81], v172, s[40:41] nt
	global_load_dwordx4 v[82:85], v172, s[42:43] nt
	s_add_i32 s55, s46, s54
	s_cmpk_lt_i32 s55, 0x800
	s_cbranch_scc0 TCV2_pro1
	s_add_i32 s47, s55, s62
	s_cmpk_lt_i32 s47, 0x800
	s_cselect_b32 s47, s47, s55
	s_and_b32 s52, s55, 0x1f
	s_lshr_b32 s53, s55, 5
	s_lshl_b32 s52, s52, 8
	s_lshl_b32 s53, s53, 19
	s_add_i32 s48, s52, s53
	s_and_b32 s52, s47, 0x1f
	s_lshr_b32 s53, s47, 5
	s_lshl_b32 s52, s52, 8
	s_lshl_b32 s53, s53, 19
	s_add_i32 s49, s52, s53
	v_add_u32_e32 v153, s48, v143
	v_add_u32_e32 v172, s49, v143
	global_load_dwordx4 v[104:107], v153, s[40:41] nt
	global_load_dwordx4 v[108:111], v153, s[42:43] nt
	global_load_dwordx4 v[112:115], v172, s[40:41] nt
	global_load_dwordx4 v[116:119], v172, s[42:43] nt
	s_waitcnt vmcnt(4)
	s_branch TCV2_bodyX
; __device__ __forceinline__ u16 f2bf(float f) { return (u16)(pk2(f, 0.f) & 0xffffu); }
; __device__ __forceinline__ u32x4 pack8(const float* f) { u32x4 w; w.x = pk2(f[0], f[1]); w.y = pk2(f[2], f[3]); w.z = pk2(f[4], f[5]); w.w = pk2(f[6], f[7]); return w; }
; __device__ void tconv(unsigned char* smem, const float* src, int ldsrc, int col0, int N, int K, u16* dst, int ldd) {
;     float* T = (float*)smem;
;     const int tid = threadIdx.x, tilesN = N >> 6, ntile = tilesN * (K >> 6);
;     const int lr = tid >> 4, lc = (tid & 15) * 4;
;     const int sn = tid >> 3, sk = (tid & 7) * 8;
;     int tile = blockIdx.x;
;     f32x4 v0 = {0.f, 0.f, 0.f, 0.f}, v1 = {0.f, 0.f, 0.f, 0.f};
;     if (tile < ntile) { const int tn = tile % tilesN, tk = tile / tilesN; const float* s = src + (size_t)(tk * 64 + lr) * ldsrc + col0 + tn * 64 + lc;
;         v0 = __builtin_nontemporal_load((const f32x4*)s); v1 = __builtin_nontemporal_load((const f32x4*)(s + (size_t)32 * ldsrc)); }
;     for (; tile < ntile; tile += gridDim.x) {
;         const int tn = tile % tilesN, tk = tile / tilesN;
; #pragma unroll
;         for (int j = 0; j < 4; ++j) { T[lr * 65 + lc + j] = v0[j]; T[(lr + 32) * 65 + lc + j] = v1[j]; }
;         asm volatile("s_waitcnt lgkmcnt(0)" ::: "memory"); __builtin_amdgcn_s_barrier(); asm volatile("" ::: "memory");
;         const int nx = tile + gridDim.x;
;         if (nx < ntile) { const int tn2 = nx % tilesN, tk2 = nx / tilesN; const float* s = src + (size_t)(tk2 * 64 + lr) * ldsrc + col0 + tn2 * 64 + lc;
;             v0 = __builtin_nontemporal_load((const f32x4*)s); v1 = __builtin_nontemporal_load((const f32x4*)(s + (size_t)32 * ldsrc)); }
;         float f[8];
; #pragma unroll
;         for (int j = 0; j < 8; ++j) f[j] = T[(sk + j) * 65 + sn];
;         *(u32x4*)(dst + (size_t)(tn * 64 + sn) * ldd + tk * 64 + sk) = pack8(f);
;         asm volatile("s_waitcnt lgkmcnt(0)" ::: "memory"); __builtin_amdgcn_s_barrier(); asm volatile("" ::: "memory");
;     }
;     __syncthreads();
; }
; __device__ void prep_small(const Params& p) {
;     const int gt = blockIdx.x * 512 + threadIdx.x, nt = gridDim.x * 512;
;     u16* LW = (u16*)(p.ws + OFF_LRUW);
;     for (int e = gt; e < 2 * 16 * 128 * 128; e += nt) { const int i = e & 127, j = (e >> 7) & 127, blk = (e >> 14) & 15, g = e >> 18;
;         LW[e] = f2bf(p.in[g ? 7 : 5][(size_t)(blk * 128 + i) * 128 + j]); }
TCV2_pro1:
	s_waitcnt vmcnt(0)
TCV2_bodyX:
	ds_write2_b32 v145, v70, v71 offset1:1
	ds_write2_b32 v145, v72, v73 offset0:2 offset1:3
	ds_write2_b32 v146, v74, v75 offset1:1
	ds_write2_b32 v146, v76, v77 offset0:2 offset1:3
	ds_write2_b32 v147, v78, v79 offset1:1
	ds_write2_b32 v147, v80, v81 offset0:2 offset1:3
	ds_write2_b32 v148, v82, v83 offset1:1
	ds_write2_b32 v148, v84, v85 offset0:2 offset1:3
	s_add_i32 s47, s46, s62
	s_cmpk_lt_i32 s47, 0x800
	s_cselect_b32 s47, s47, s46
	s_and_b32 s52, s46, 0x1f
	s_lshr_b32 s53, s46, 5
	s_lshl_b32 s52, s52, 19
	s_lshl_b32 s53, s53, 7
	s_add_i32 s50, s52, s53
	s_and_b32 s52, s47, 0x1f
	s_lshr_b32 s53, s47, 5
	s_lshl_b32 s52, s52, 19
	s_lshl_b32 s53, s53, 7
	s_add_i32 s51, s52, s53
	s_waitcnt lgkmcnt(0)
	s_barrier
	s_add_i32 s55, s46, s54
	s_add_i32 s55, s55, s54
	s_cmpk_lt_i32 s55, 0x800
	s_cbranch_scc0 TCV2_noloadX
	s_add_i32 s47, s55, s62
	s_cmpk_lt_i32 s47, 0x800
	s_cselect_b32 s47, s47, s55
	s_and_b32 s52, s55, 0x1f
	s_lshr_b32 s53, s55, 5
	s_lshl_b32 s52, s52, 8
	s_lshl_b32 s53, s53, 19
	s_add_i32 s48, s52, s53
	s_and_b32 s52, s47, 0x1f
	s_lshr_b32 s53, s47, 5
	s_lshl_b32 s52, s52, 8
	s_lshl_b32 s53, s53, 19
	s_add_i32 s49, s52, s53
	v_add_u32_e32 v153, s48, v143
	v_add_u32_e32 v172, s49, v143
	global_load_dwordx4 v[70:73], v153, s[40:41] nt
	global_load_dwordx4 v[74:77], v153, s[42:43] nt
	global_load_dwordx4 v[78:81], v172, s[40:41] nt
	global_load_dwordx4 v[82:85], v172, s[42:43] nt
TCV2_noloadX:
	ds_read2_b32 v[156:157], v149 offset1:65
	ds_read2_b32 v[158:159], v149 offset0:130 offset1:195
	ds_read2_b32 v[160:161], v150 offset0:4 offset1:69
	ds_read2_b32 v[162:163], v150 offset0:134 offset1:199
	ds_read2_b32 v[164:165], v151 offset1:65
	ds_read2_b32 v[166:167], v151 offset0:130 offset1:195
	ds_read2_b32 v[168:169], v152 offset0:4 offset1:69
	ds_read2_b32 v[170:171], v152 offset0:134 offset1:199
	v_add_u32_e32 v154, s50, v144
	v_add_u32_e32 v155, s51, v144
	s_waitcnt lgkmcnt(7)
	v_cvt_pk_bf16_f32 v156, v156, v157
	s_waitcnt lgkmcnt(6)
	v_cvt_pk_bf16_f32 v157, v158, v159
	s_waitcnt lgkmcnt(5)
	v_cvt_pk_bf16_f32 v158, v160, v161
	s_waitcnt lgkmcnt(4)
	v_cvt_pk_bf16_f32 v159, v162, v163
	global_store_dwordx4 v154, v[156:159], s[44:45]
	s_waitcnt lgkmcnt(3)
	v_cvt_pk_bf16_f32 v164, v164, v165
	s_waitcnt lgkmcnt(2)
	v_cvt_pk_bf16_f32 v165, v166, v167
	s_waitcnt lgkmcnt(1)
	v_cvt_pk_bf16_f32 v166, v168, v169
	s_waitcnt lgkmcnt(0)
	v_cvt_pk_bf16_f32 v167, v170, v171
	global_store_dwordx4 v155, v[164:167], s[44:45]
	s_add_i32 s46, s46, s54
	s_cmpk_lt_i32 s46, 0x800
	s_cbranch_scc0 TCV2_exit
	s_cmpk_lt_i32 s55, 0x800
	s_cbranch_scc1 TCV2_w6X
	s_waitcnt vmcnt(2)
TCV2_w6X:
	s_waitcnt vmcnt(6)
TCV2_bodyY:
	ds_write2_b32 v173, v104, v105 offset1:1
	ds_write2_b32 v173, v106, v107 offset0:2 offset1:3
	ds_write2_b32 v174, v108, v109 offset1:1
	ds_write2_b32 v174, v110, v111 offset0:2 offset1:3
	ds_write2_b32 v175, v112, v113 offset1:1
	ds_write2_b32 v175, v114, v115 offset0:2 offset1:3
	ds_write2_b32 v176, v116, v117 offset1:1
	ds_write2_b32 v176, v118, v119 offset0:2 offset1:3
	s_add_i32 s47, s46, s62
	s_cmpk_lt_i32 s47, 0x800
	s_cselect_b32 s47, s47, s46
	s_and_b32 s52, s46, 0x1f
	s_lshr_b32 s53, s46, 5
	s_lshl_b32 s52, s52, 19
	s_lshl_b32 s53, s53, 7
	s_add_i32 s50, s52, s53
	s_and_b32 s52, s47, 0x1f
	s_lshr_b32 s53, s47, 5
	s_lshl_b32 s52, s52, 19
	s_lshl_b32 s53, s53, 7
	s_add_i32 s51, s52, s53
	s_waitcnt lgkmcnt(0)
	s_barrier
	s_add_i32 s55, s46, s54
	s_add_i32 s55, s55, s54
	s_cmpk_lt_i32 s55, 0x800
	s_cbranch_scc0 TCV2_noloadY
	s_add_i32 s47, s55, s62
	s_cmpk_lt_i32 s47, 0x800
	s_cselect_b32 s47, s47, s55
	s_and_b32 s52, s55, 0x1f
	s_lshr_b32 s53, s55, 5
	s_lshl_b32 s52, s52, 8
	s_lshl_b32 s53, s53, 19
	s_add_i32 s48, s52, s53
	s_and_b32 s52, s47, 0x1f
	s_lshr_b32 s53, s47, 5
	s_lshl_b32 s52, s52, 8
	s_lshl_b32 s53, s53, 19
	s_add_i32 s49, s52, s53
	v_add_u32_e32 v153, s48, v143
	v_add_u32_e32 v172, s49, v143
	global_load_dwordx4 v[104:107], v153, s[40:41] nt
	global_load_dwordx4 v[108:111], v153, s[42:43] nt
	global_load_dwordx4 v[112:115], v172, s[40:41] nt
	global_load_dwordx4 v[116:119], v172, s[42:43] nt
TCV2_noloadY:
	ds_read2_b32 v[156:157], v177 offset1:65
	ds_read2_b32 v[158:159], v177 offset0:130 offset1:195
	ds_read2_b32 v[160:161], v178 offset0:4 offset1:69
	ds_read2_b32 v[162:163], v178 offset0:134 offset1:199
	ds_read2_b32 v[164:165], v120 offset1:65
	ds_read2_b32 v[166:167], v120 offset0:130 offset1:195
	ds_read2_b32 v[168:169], v121 offset0:4 offset1:69
	ds_read2_b32 v[170:171], v121 offset0:134 offset1:199
	v_add_u32_e32 v154, s50, v144
	v_add_u32_e32 v155, s51, v144
	s_waitcnt lgkmcnt(7)
	v_cvt_pk_bf16_f32 v156, v156, v157
	s_waitcnt lgkmcnt(6)
	v_cvt_pk_bf16_f32 v157, v158, v159
	s_waitcnt lgkmcnt(5)
	v_cvt_pk_bf16_f32 v158, v160, v161
	s_waitcnt lgkmcnt(4)
	v_cvt_pk_bf16_f32 v159, v162, v163
	global_store_dwordx4 v154, v[156:159], s[44:45]
	s_waitcnt lgkmcnt(3)
	v_cvt_pk_bf16_f32 v164, v164, v165
	s_waitcnt lgkmcnt(2)
	v_cvt_pk_bf16_f32 v165, v166, v167
	s_waitcnt lgkmcnt(1)
	v_cvt_pk_bf16_f32 v166, v168, v169
	s_waitcnt lgkmcnt(0)
	v_cvt_pk_bf16_f32 v167, v170, v171
	global_store_dwordx4 v155, v[164:167], s[44:45]
	s_add_i32 s46, s46, s54
	s_cmpk_lt_i32 s46, 0x800
	s_cbranch_scc0 TCV2_exit
	s_cmpk_lt_i32 s55, 0x800
	s_cbranch_scc1 TCV2_w6Y
	s_waitcnt vmcnt(2)
TCV2_w6Y:
	s_waitcnt vmcnt(6)
	s_branch TCV2_bodyX
TCV2_exit:
.LBB0_15:
	s_waitcnt vmcnt(2)
	v_lshl_add_u32 v2, s70, 9, v1
	s_mov_b32 s3, 0x80000
	s_lshl_b32 s2, s62, 9
	v_cmp_gt_i32_e32 vcc, s3, v2
	s_barrier
	s_and_saveexec_b64 s[4:5], vcc
	s_cbranch_execz .LBB0_18
	v_ashrrev_i32_e32 v3, 31, v2
	v_readlane_b32 s12, v251, 0
	v_lshl_add_u64 v[4:5], v[2:3], 1, s[64:65]
	s_mov_b64 s[6:7], 0x1f700000
	s_ashr_i32 s3, s2, 31
	v_lshlrev_b32_e32 v3, 7, v1
	v_readlane_b32 s18, v251, 6
	v_readlane_b32 s19, v251, 7
	v_readlane_b32 s22, v251, 10
	v_readlane_b32 s23, v251, 11
	v_lshl_add_u64 v[4:5], v[4:5], 0, s[6:7]
	s_lshl_b64 s[6:7], s[2:3], 1
	v_lshl_add_u32 v3, s70, 16, v3
	s_lshl_b32 s3, s62, 16
	s_mov_b64 s[8:9], 0
	s_mov_b32 s10, 0x40000
	s_waitcnt vmcnt(1)
	v_mov_b32_e32 v8, s23
	v_mov_b32_e32 v9, s19
	v_mov_b32_e32 v10, s22
	v_mov_b32_e32 v11, s18
	v_mov_b32_e32 v7, 0
	s_mov_b32 s11, 0x7ffff
	v_mov_b32_e32 v12, v2
	v_readlane_b32 s13, v251, 1
	v_readlane_b32 s14, v251, 2
	v_readlane_b32 s15, v251, 3
	v_readlane_b32 s16, v251, 4
	v_readlane_b32 s17, v251, 5
	v_readlane_b32 s20, v251, 8
	v_readlane_b32 s21, v251, 9
	v_readlane_b32 s24, v251, 12
	v_readlane_b32 s25, v251, 13
	v_readlane_b32 s26, v251, 14
	v_readlane_b32 s27, v251, 15

; __device__ __forceinline__ u32x4 pack8(const float* f) { u32x4 w; w.x = pk2(f[0], f[1]); w.y = pk2(f[2], f[3]); w.z = pk2(f[4], f[5]); w.w = pk2(f[6], f[7]); return w; }
; __device__ void tconv(unsigned char* smem, const float* src, int ldsrc, int col0, int N, int K, u16* dst, int ldd) {
;     float* T = (float*)smem;
;     const int tid = threadIdx.x, tilesN = N >> 6, ntile = tilesN * (K >> 6);
;     const int lr = tid >> 4, lc = (tid & 15) * 4;
;     const int sn = tid >> 3, sk = (tid & 7) * 8;
;     int tile = blockIdx.x;
;     f32x4 v0 = {0.f, 0.f, 0.f, 0.f}, v1 = {0.f, 0.f, 0.f, 0.f};
;     if (tile < ntile) { const int tn = tile % tilesN, tk = tile / tilesN; const float* s = src + (size_t)(tk * 64 + lr) * ldsrc + col0 + tn * 64 + lc;
;         v0 = __builtin_nontemporal_load((const f32x4*)s); v1 = __builtin_nontemporal_load((const f32x4*)(s + (size_t)32 * ldsrc)); }
;     for (; tile < ntile; tile += gridDim.x) {
;         const int tn = tile % tilesN, tk = tile / tilesN;
; #pragma unroll
;         for (int j = 0; j < 4; ++j) { T[lr * 65 + lc + j] = v0[j]; T[(lr + 32) * 65 + lc + j] = v1[j]; }
;         asm volatile("s_waitcnt lgkmcnt(0)" ::: "memory"); __builtin_amdgcn_s_barrier(); asm volatile("" ::: "memory");
;         const int nx = tile + gridDim.x;
;         if (nx < ntile) { const int tn2 = nx % tilesN, tk2 = nx / tilesN; const float* s = src + (size_t)(tk2 * 64 + lr) * ldsrc + col0 + tn2 * 64 + lc;
;             v0 = __builtin_nontemporal_load((const f32x4*)s); v1 = __builtin_nontemporal_load((const f32x4*)(s + (size_t)32 * ldsrc)); }
;         float f[8];
; #pragma unroll
;         for (int j = 0; j < 8; ++j) f[j] = T[(sk + j) * 65 + sn];
;         *(u32x4*)(dst + (size_t)(tn * 64 + sn) * ldd + tk * 64 + sk) = pack8(f);
;         asm volatile("s_waitcnt lgkmcnt(0)" ::: "memory"); __builtin_amdgcn_s_barrier(); asm volatile("" ::: "memory");
;     }
;     __syncthreads();
; }
.LBB0_617:
	s_cmpk_gt_i32 s70, 0xfff
	s_cbranch_scc1 .LBB0_624
	s_waitcnt vmcnt(0) lgkmcnt(0)
	s_barrier
	v_readlane_b32 s56, v251, 32
	v_readlane_b32 s57, v251, 33
	v_and_b32_e32 v142, 0x3ff, v0
	v_lshrrev_b32_e32 v153, 4, v142
	v_and_b32_e32 v154, 15, v142
	v_lshlrev_b32_e32 v154, 4, v154
	v_lshlrev_b32_e32 v143, 16, v153
	s_load_dwordx2 s[40:41], s[56:57], 0xc0
	v_add_u32_e32 v143, v143, v154
	v_mul_u32_u24_e32 v145, 0x104, v153
	v_add_u32_e32 v145, v145, v154
	v_add_u32_e32 v146, 0x2080, v145
	v_add_u32_e32 v147, 0x4100, v145
	v_add_u32_e32 v148, 0x6180, v145
	v_lshrrev_b32_e32 v153, 3, v142
	v_and_b32_e32 v154, 7, v142
	v_mul_u32_u24_e32 v149, 0x820, v154
	v_lshl_add_u32 v149, v153, 2, v149
	v_add_u32_e32 v150, 0x400, v149
	v_add_u32_e32 v151, 0x4100, v149
	v_add_u32_e32 v152, 0x4500, v149
	v_add_u32_e32 v173, 0x8200, v145
	v_add_u32_e32 v174, 0x8200, v146
	v_add_u32_e32 v175, 0x8200, v147
	v_add_u32_e32 v176, 0x8200, v148
	v_add_u32_e32 v177, 0x8200, v149
	v_add_u32_e32 v178, 0x8200, v150
	v_add_u32_e32 v120, 0x8200, v151
	v_add_u32_e32 v121, 0x8200, v152
	v_lshlrev_b32_e32 v144, 12, v153
	v_lshl_add_u32 v144, v154, 4, v144
	s_add_u32 s44, s64, 0x1c000000
	s_addc_u32 s45, s65, 0
	s_lshl_b32 s54, s62, 1
	s_mov_b32 s46, s70
	s_waitcnt lgkmcnt(0)
	s_add_u32 s42, s40, 0x200000
	s_addc_u32 s43, s41, 0
	s_add_i32 s47, s46, s62
	s_cmpk_lt_i32 s47, 0x1000
	s_cselect_b32 s47, s47, s46
	s_and_b32 s52, s46, 0x7f
	s_lshr_b32 s53, s46, 7
	s_lshl_b32 s52, s52, 8
	s_lshl_b32 s53, s53, 22
	s_add_i32 s48, s52, s53
	s_and_b32 s52, s47, 0x7f
	s_lshr_b32 s53, s47, 7
	s_lshl_b32 s52, s52, 8
	s_lshl_b32 s53, s53, 22
	s_add_i32 s49, s52, s53
	v_add_u32_e32 v153, s48, v143
	v_add_u32_e32 v172, s49, v143
	global_load_dwordx4 v[70:73], v153, s[40:41] nt
	global_load_dwordx4 v[74:77], v153, s[42:43] nt
	global_load_dwordx4 v[78:81], v172, s[40:41] nt
	global_load_dwordx4 v[82:85], v172, s[42:43] nt
	s_add_i32 s55, s46, s54
	s_cmpk_lt_i32 s55, 0x1000
	s_cbranch_scc0 TCV3_pro1
	s_add_i32 s47, s55, s62
	s_cmpk_lt_i32 s47, 0x1000
	s_cselect_b32 s47, s47, s55
	s_and_b32 s52, s55, 0x7f
	s_lshr_b32 s53, s55, 7
	s_lshl_b32 s52, s52, 8
	s_lshl_b32 s53, s53, 22
	s_add_i32 s48, s52, s53
	s_and_b32 s52, s47, 0x7f
	s_lshr_b32 s53, s47, 7
	s_lshl_b32 s52, s52, 8
	s_lshl_b32 s53, s53, 22
	s_add_i32 s49, s52, s53
	v_add_u32_e32 v153, s48, v143
	v_add_u32_e32 v172, s49, v143
	global_load_dwordx4 v[104:107], v153, s[40:41] nt
	global_load_dwordx4 v[108:111], v153, s[42:43] nt
	global_load_dwordx4 v[112:115], v172, s[40:41] nt
	global_load_dwordx4 v[116:119], v172, s[42:43] nt
	s_waitcnt vmcnt(4)
	s_branch TCV3_bodyX
TCV3_pro1:
	s_waitcnt vmcnt(0)
TCV3_bodyX:
	ds_write2_b32 v145, v70, v71 offset1:1
	ds_write2_b32 v145, v72, v73 offset0:2 offset1:3
	ds_write2_b32 v146, v74, v75 offset1:1
	ds_write2_b32 v146, v76, v77 offset0:2 offset1:3
	ds_write2_b32 v147, v78, v79 offset1:1
	ds_write2_b32 v147, v80, v81 offset0:2 offset1:3
	ds_write2_b32 v148, v82, v83 offset1:1
	ds_write2_b32 v148, v84, v85 offset0:2 offset1:3
	s_add_i32 s47, s46, s62
	s_cmpk_lt_i32 s47, 0x1000
	s_cselect_b32 s47, s47, s46
	s_and_b32 s52, s46, 0x7f
	s_lshr_b32 s53, s46, 7
	s_lshl_b32 s52, s52, 18
	s_lshl_b32 s53, s53, 7
	s_add_i32 s50, s52, s53
	s_and_b32 s52, s47, 0x7f
	s_lshr_b32 s53, s47, 7
	s_lshl_b32 s52, s52, 18
	s_lshl_b32 s53, s53, 7
	s_add_i32 s51, s52, s53
	s_waitcnt lgkmcnt(0)
	s_barrier
	s_add_i32 s55, s46, s54
	s_add_i32 s55, s55, s54
	s_cmpk_lt_i32 s55, 0x1000
	s_cbranch_scc0 TCV3_noloadX
	s_add_i32 s47, s55, s62
	s_cmpk_lt_i32 s47, 0x1000
	s_cselect_b32 s47, s47, s55
	s_and_b32 s52, s55, 0x7f
	s_lshr_b32 s53, s55, 7
	s_lshl_b32 s52, s52, 8
	s_lshl_b32 s53, s53, 22
	s_add_i32 s48, s52, s53
	s_and_b32 s52, s47, 0x7f
	s_lshr_b32 s53, s47, 7
	s_lshl_b32 s52, s52, 8
	s_lshl_b32 s53, s53, 22
	s_add_i32 s49, s52, s53
	v_add_u32_e32 v153, s48, v143
	v_add_u32_e32 v172, s49, v143
	global_load_dwordx4 v[70:73], v153, s[40:41] nt
	global_load_dwordx4 v[74:77], v153, s[42:43] nt
	global_load_dwordx4 v[78:81], v172, s[40:41] nt
	global_load_dwordx4 v[82:85], v172, s[42:43] nt
; __device__ __forceinline__ u32x4 pack8(const float* f) { u32x4 w; w.x = pk2(f[0], f[1]); w.y = pk2(f[2], f[3]); w.z = pk2(f[4], f[5]); w.w = pk2(f[6], f[7]); return w; }
; __device__ void tconv(unsigned char* smem, const float* src, int ldsrc, int col0, int N, int K, u16* dst, int ldd) {
;     float* T = (float*)smem;
;     const int tid = threadIdx.x, tilesN = N >> 6, ntile = tilesN * (K >> 6);
;     const int lr = tid >> 4, lc = (tid & 15) * 4;
;     const int sn = tid >> 3, sk = (tid & 7) * 8;
;     int tile = blockIdx.x;
;     f32x4 v0 = {0.f, 0.f, 0.f, 0.f}, v1 = {0.f, 0.f, 0.f, 0.f};
;     if (tile < ntile) { const int tn = tile % tilesN, tk = tile / tilesN; const float* s = src + (size_t)(tk * 64 + lr) * ldsrc + col0 + tn * 64 + lc;
;         v0 = __builtin_nontemporal_load((const f32x4*)s); v1 = __builtin_nontemporal_load((const f32x4*)(s + (size_t)32 * ldsrc)); }
;     for (; tile < ntile; tile += gridDim.x) {
;         const int tn = tile % tilesN, tk = tile / tilesN;
; #pragma unroll
;         for (int j = 0; j < 4; ++j) { T[lr * 65 + lc + j] = v0[j]; T[(lr + 32) * 65 + lc + j] = v1[j]; }
;         asm volatile("s_waitcnt lgkmcnt(0)" ::: "memory"); __builtin_amdgcn_s_barrier(); asm volatile("" ::: "memory");
;         const int nx = tile + gridDim.x;
;         if (nx < ntile) { const int tn2 = nx % tilesN, tk2 = nx / tilesN; const float* s = src + (size_t)(tk2 * 64 + lr) * ldsrc + col0 + tn2 * 64 + lc;
;             v0 = __builtin_nontemporal_load((const f32x4*)s); v1 = __builtin_nontemporal_load((const f32x4*)(s + (size_t)32 * ldsrc)); }
;         float f[8];
; #pragma unroll
;         for (int j = 0; j < 8; ++j) f[j] = T[(sk + j) * 65 + sn];
;         *(u32x4*)(dst + (size_t)(tn * 64 + sn) * ldd + tk * 64 + sk) = pack8(f);
;         asm volatile("s_waitcnt lgkmcnt(0)" ::: "memory"); __builtin_amdgcn_s_barrier(); asm volatile("" ::: "memory");
;     }
;     __syncthreads();
; }
TCV3_noloadX:
	ds_read2_b32 v[156:157], v149 offset1:65
	ds_read2_b32 v[158:159], v149 offset0:130 offset1:195
	ds_read2_b32 v[160:161], v150 offset0:4 offset1:69
	ds_read2_b32 v[162:163], v150 offset0:134 offset1:199
	ds_read2_b32 v[164:165], v151 offset1:65
	ds_read2_b32 v[166:167], v151 offset0:130 offset1:195
	ds_read2_b32 v[168:169], v152 offset0:4 offset1:69
	ds_read2_b32 v[170:171], v152 offset0:134 offset1:199
	v_add_u32_e32 v154, s50, v144
	v_add_u32_e32 v155, s51, v144
	s_waitcnt lgkmcnt(7)
	v_cvt_pk_bf16_f32 v156, v156, v157
	s_waitcnt lgkmcnt(6)
	v_cvt_pk_bf16_f32 v157, v158, v159
	s_waitcnt lgkmcnt(5)
	v_cvt_pk_bf16_f32 v158, v160, v161
	s_waitcnt lgkmcnt(4)
	v_cvt_pk_bf16_f32 v159, v162, v163
	global_store_dwordx4 v154, v[156:159], s[44:45]
	s_waitcnt lgkmcnt(3)
	v_cvt_pk_bf16_f32 v164, v164, v165
	s_waitcnt lgkmcnt(2)
	v_cvt_pk_bf16_f32 v165, v166, v167
	s_waitcnt lgkmcnt(1)
	v_cvt_pk_bf16_f32 v166, v168, v169
	s_waitcnt lgkmcnt(0)
	v_cvt_pk_bf16_f32 v167, v170, v171
	global_store_dwordx4 v155, v[164:167], s[44:45]
	s_add_i32 s46, s46, s54
	s_cmpk_lt_i32 s46, 0x1000
	s_cbranch_scc0 TCV3_exit
	s_cmpk_lt_i32 s55, 0x1000
	s_cbranch_scc1 TCV3_w6X
	s_waitcnt vmcnt(2)
TCV3_w6X:
	s_waitcnt vmcnt(6)
TCV3_bodyY:
	ds_write2_b32 v173, v104, v105 offset1:1
	ds_write2_b32 v173, v106, v107 offset0:2 offset1:3
	ds_write2_b32 v174, v108, v109 offset1:1
	ds_write2_b32 v174, v110, v111 offset0:2 offset1:3
	ds_write2_b32 v175, v112, v113 offset1:1
	ds_write2_b32 v175, v114, v115 offset0:2 offset1:3
	ds_write2_b32 v176, v116, v117 offset1:1
	ds_write2_b32 v176, v118, v119 offset0:2 offset1:3
	s_add_i32 s47, s46, s62
	s_cmpk_lt_i32 s47, 0x1000
	s_cselect_b32 s47, s47, s46
	s_and_b32 s52, s46, 0x7f
	s_lshr_b32 s53, s46, 7
	s_lshl_b32 s52, s52, 18
	s_lshl_b32 s53, s53, 7
	s_add_i32 s50, s52, s53
	s_and_b32 s52, s47, 0x7f
	s_lshr_b32 s53, s47, 7
	s_lshl_b32 s52, s52, 18
	s_lshl_b32 s53, s53, 7
	s_add_i32 s51, s52, s53
	s_waitcnt lgkmcnt(0)
	s_barrier
	s_add_i32 s55, s46, s54
	s_add_i32 s55, s55, s54
	s_cmpk_lt_i32 s55, 0x1000
	s_cbranch_scc0 TCV3_noloadY
	s_add_i32 s47, s55, s62
	s_cmpk_lt_i32 s47, 0x1000
	s_cselect_b32 s47, s47, s55
	s_and_b32 s52, s55, 0x7f
	s_lshr_b32 s53, s55, 7
	s_lshl_b32 s52, s52, 8
	s_lshl_b32 s53, s53, 22
	s_add_i32 s48, s52, s53
	s_and_b32 s52, s47, 0x7f
	s_lshr_b32 s53, s47, 7
	s_lshl_b32 s52, s52, 8
	s_lshl_b32 s53, s53, 22
	s_add_i32 s49, s52, s53
	v_add_u32_e32 v153, s48, v143
	v_add_u32_e32 v172, s49, v143
	global_load_dwordx4 v[104:107], v153, s[40:41] nt
	global_load_dwordx4 v[108:111], v153, s[42:43] nt
	global_load_dwordx4 v[112:115], v172, s[40:41] nt
	global_load_dwordx4 v[116:119], v172, s[42:43] nt
TCV3_noloadY:
	ds_read2_b32 v[156:157], v177 offset1:65
	ds_read2_b32 v[158:159], v177 offset0:130 offset1:195
	ds_read2_b32 v[160:161], v178 offset0:4 offset1:69
	ds_read2_b32 v[162:163], v178 offset0:134 offset1:199
	ds_read2_b32 v[164:165], v120 offset1:65
	ds_read2_b32 v[166:167], v120 offset0:130 offset1:195
	ds_read2_b32 v[168:169], v121 offset0:4 offset1:69
	ds_read2_b32 v[170:171], v121 offset0:134 offset1:199
	v_add_u32_e32 v154, s50, v144
	v_add_u32_e32 v155, s51, v144
	s_waitcnt lgkmcnt(7)
	v_cvt_pk_bf16_f32 v156, v156, v157
	s_waitcnt lgkmcnt(6)
	v_cvt_pk_bf16_f32 v157, v158, v159
	s_waitcnt lgkmcnt(5)
	v_cvt_pk_bf16_f32 v158, v160, v161
	s_waitcnt lgkmcnt(4)
	v_cvt_pk_bf16_f32 v159, v162, v163
	global_store_dwordx4 v154, v[156:159], s[44:45]
	s_waitcnt lgkmcnt(3)
	v_cvt_pk_bf16_f32 v164, v164, v165
	s_waitcnt lgkmcnt(2)
	v_cvt_pk_bf16_f32 v165, v166, v167
	s_waitcnt lgkmcnt(1)
	v_cvt_pk_bf16_f32 v166, v168, v169
	s_waitcnt lgkmcnt(0)
	v_cvt_pk_bf16_f32 v167, v170, v171
	global_store_dwordx4 v155, v[164:167], s[44:45]
	s_add_i32 s46, s46, s54
	s_cmpk_lt_i32 s46, 0x1000
	s_cbranch_scc0 TCV3_exit
	s_cmpk_lt_i32 s55, 0x1000
	s_cbranch_scc1 TCV3_w6Y
	s_waitcnt vmcnt(2)
TCV3_w6Y:
	s_waitcnt vmcnt(6)
	s_branch TCV3_bodyX
TCV3_exit:
.LBB0_624:
	s_waitcnt lgkmcnt(0)
	s_barrier

; __device__ __forceinline__ u32x4 pack8(const float* f) { u32x4 w; w.x = pk2(f[0], f[1]); w.y = pk2(f[2], f[3]); w.z = pk2(f[4], f[5]); w.w = pk2(f[6], f[7]); return w; }
; __device__ void tconv(unsigned char* smem, const float* src, int ldsrc, int col0, int N, int K, u16* dst, int ldd) {
;     float* T = (float*)smem;
;     const int tid = threadIdx.x, tilesN = N >> 6, ntile = tilesN * (K >> 6);
;     const int lr = tid >> 4, lc = (tid & 15) * 4;
;     const int sn = tid >> 3, sk = (tid & 7) * 8;
;     int tile = blockIdx.x;
;     f32x4 v0 = {0.f, 0.f, 0.f, 0.f}, v1 = {0.f, 0.f, 0.f, 0.f};
;     if (tile < ntile) { const int tn = tile % tilesN, tk = tile / tilesN; const float* s = src + (size_t)(tk * 64 + lr) * ldsrc + col0 + tn * 64 + lc;
;         v0 = __builtin_nontemporal_load((const f32x4*)s); v1 = __builtin_nontemporal_load((const f32x4*)(s + (size_t)32 * ldsrc)); }
;     for (; tile < ntile; tile += gridDim.x) {
;         const int tn = tile % tilesN, tk = tile / tilesN;
; #pragma unroll
;         for (int j = 0; j < 4; ++j) { T[lr * 65 + lc + j] = v0[j]; T[(lr + 32) * 65 + lc + j] = v1[j]; }
;         asm volatile("s_waitcnt lgkmcnt(0)" ::: "memory"); __builtin_amdgcn_s_barrier(); asm volatile("" ::: "memory");
;         const int nx = tile + gridDim.x;
;         if (nx < ntile) { const int tn2 = nx % tilesN, tk2 = nx / tilesN; const float* s = src + (size_t)(tk2 * 64 + lr) * ldsrc + col0 + tn2 * 64 + lc;
;             v0 = __builtin_nontemporal_load((const f32x4*)s); v1 = __builtin_nontemporal_load((const f32x4*)(s + (size_t)32 * ldsrc)); }
;         float f[8];
; #pragma unroll
;         for (int j = 0; j < 8; ++j) f[j] = T[(sk + j) * 65 + sn];
;         *(u32x4*)(dst + (size_t)(tn * 64 + sn) * ldd + tk * 64 + sk) = pack8(f);
;         asm volatile("s_waitcnt lgkmcnt(0)" ::: "memory"); __builtin_amdgcn_s_barrier(); asm volatile("" ::: "memory");
;     }
;     __syncthreads();
; }
.LBB0_674:
	s_or_b64 exec, exec, s[2:3]
	s_cmpk_gt_i32 s70, 0x7ff
	s_cbranch_scc1 .LBB0_681
	s_waitcnt vmcnt(0) lgkmcnt(0)
	s_barrier
	v_readlane_b32 s56, v251, 32
	v_readlane_b32 s57, v251, 33
	v_and_b32_e32 v142, 0x3ff, v0
	v_lshrrev_b32_e32 v153, 4, v142
	v_and_b32_e32 v154, 15, v142
	v_lshlrev_b32_e32 v154, 4, v154
	v_lshlrev_b32_e32 v143, 16, v153
	s_load_dwordx2 s[40:41], s[56:57], 0xc0
	v_add_u32_e32 v143, v143, v154
	v_mul_u32_u24_e32 v145, 0x104, v153
	v_add_u32_e32 v145, v145, v154
	v_add_u32_e32 v146, 0x2080, v145
	v_add_u32_e32 v147, 0x4100, v145
	v_add_u32_e32 v148, 0x6180, v145
	v_lshrrev_b32_e32 v153, 3, v142
	v_and_b32_e32 v154, 7, v142
	v_mul_u32_u24_e32 v149, 0x820, v154
	v_lshl_add_u32 v149, v153, 2, v149
	v_add_u32_e32 v150, 0x400, v149
	v_add_u32_e32 v151, 0x4100, v149
	v_add_u32_e32 v152, 0x4500, v149
	v_add_u32_e32 v173, 0x8200, v145
	v_add_u32_e32 v174, 0x8200, v146
	v_add_u32_e32 v175, 0x8200, v147
	v_add_u32_e32 v176, 0x8200, v148
	v_add_u32_e32 v177, 0x8200, v149
	v_add_u32_e32 v178, 0x8200, v150
	v_add_u32_e32 v120, 0x8200, v151
	v_add_u32_e32 v121, 0x8200, v152
	v_lshlrev_b32_e32 v144, 12, v153
	v_lshl_add_u32 v144, v154, 4, v144
	s_add_u32 s44, s64, 0x1e000000
	s_addc_u32 s45, s65, 0
	s_lshl_b32 s54, s62, 1
	s_mov_b32 s46, s70
	s_waitcnt lgkmcnt(0)
	s_add_u32 s40, s40, 0x8000
	s_addc_u32 s41, s41, 0
	s_add_u32 s42, s40, 0x200000
	s_addc_u32 s43, s41, 0
	s_add_i32 s47, s46, s62
	s_cmpk_lt_i32 s47, 0x800
	s_cselect_b32 s47, s47, s46
	s_and_b32 s52, s46, 0x3f
	s_lshr_b32 s53, s46, 6
	s_lshl_b32 s52, s52, 8
	s_lshl_b32 s53, s53, 22
	s_add_i32 s48, s52, s53
	s_and_b32 s52, s47, 0x3f
	s_lshr_b32 s53, s47, 6
	s_lshl_b32 s52, s52, 8
	s_lshl_b32 s53, s53, 22
	s_add_i32 s49, s52, s53
	v_add_u32_e32 v153, s48, v143
	v_add_u32_e32 v172, s49, v143
	global_load_dwordx4 v[70:73], v153, s[40:41] nt
	global_load_dwordx4 v[74:77], v153, s[42:43] nt
	global_load_dwordx4 v[78:81], v172, s[40:41] nt
	global_load_dwordx4 v[82:85], v172, s[42:43] nt
	s_add_i32 s55, s46, s54
	s_cmpk_lt_i32 s55, 0x800
	s_cbranch_scc0 TCV4_pro1
	s_add_i32 s47, s55, s62
	s_cmpk_lt_i32 s47, 0x800
	s_cselect_b32 s47, s47, s55
	s_and_b32 s52, s55, 0x3f
	s_lshr_b32 s53, s55, 6
	s_lshl_b32 s52, s52, 8
	s_lshl_b32 s53, s53, 22
	s_add_i32 s48, s52, s53
	s_and_b32 s52, s47, 0x3f
	s_lshr_b32 s53, s47, 6
	s_lshl_b32 s52, s52, 8
	s_lshl_b32 s53, s53, 22
	s_add_i32 s49, s52, s53
	v_add_u32_e32 v153, s48, v143
	v_add_u32_e32 v172, s49, v143
	global_load_dwordx4 v[104:107], v153, s[40:41] nt
	global_load_dwordx4 v[108:111], v153, s[42:43] nt
	global_load_dwordx4 v[112:115], v172, s[40:41] nt
	global_load_dwordx4 v[116:119], v172, s[42:43] nt
	s_waitcnt vmcnt(4)
	s_branch TCV4_bodyX
TCV4_pro1:
	s_waitcnt vmcnt(0)
TCV4_bodyX:
	ds_write2_b32 v145, v70, v71 offset1:1
	ds_write2_b32 v145, v72, v73 offset0:2 offset1:3
	ds_write2_b32 v146, v74, v75 offset1:1
	ds_write2_b32 v146, v76, v77 offset0:2 offset1:3
	ds_write2_b32 v147, v78, v79 offset1:1
	ds_write2_b32 v147, v80, v81 offset0:2 offset1:3
	ds_write2_b32 v148, v82, v83 offset1:1
	ds_write2_b32 v148, v84, v85 offset0:2 offset1:3
	s_add_i32 s47, s46, s62
	s_cmpk_lt_i32 s47, 0x800
	s_cselect_b32 s47, s47, s46
	s_and_b32 s52, s46, 0x3f
	s_lshr_b32 s53, s46, 6
	s_lshl_b32 s52, s52, 18
	s_lshl_b32 s53, s53, 7
	s_add_i32 s50, s52, s53
	s_and_b32 s52, s47, 0x3f
	s_lshr_b32 s53, s47, 6
	s_lshl_b32 s52, s52, 18
	s_lshl_b32 s53, s53, 7
	s_add_i32 s51, s52, s53
	s_waitcnt lgkmcnt(0)
	s_barrier
	s_add_i32 s55, s46, s54
	s_add_i32 s55, s55, s54
	s_cmpk_lt_i32 s55, 0x800
	s_cbranch_scc0 TCV4_noloadX
	s_add_i32 s47, s55, s62
	s_cmpk_lt_i32 s47, 0x800
	s_cselect_b32 s47, s47, s55
	s_and_b32 s52, s55, 0x3f
	s_lshr_b32 s53, s55, 6
	s_lshl_b32 s52, s52, 8
	s_lshl_b32 s53, s53, 22
	s_add_i32 s48, s52, s53
	s_and_b32 s52, s47, 0x3f
	s_lshr_b32 s53, s47, 6
	s_lshl_b32 s52, s52, 8
	s_lshl_b32 s53, s53, 22
	s_add_i32 s49, s52, s53
	v_add_u32_e32 v153, s48, v143
	v_add_u32_e32 v172, s49, v143
	global_load_dwordx4 v[70:73], v153, s[40:41] nt
	global_load_dwordx4 v[74:77], v153, s[42:43] nt
	global_load_dwordx4 v[78:81], v172, s[40:41] nt
	global_load_dwordx4 v[82:85], v172, s[42:43] nt
; __device__ void tconv(unsigned char* smem, const float* src, int ldsrc, int col0, int N, int K, u16* dst, int ldd) {
;     float* T = (float*)smem;
;     const int tid = threadIdx.x, tilesN = N >> 6, ntile = tilesN * (K >> 6);
;     const int lr = tid >> 4, lc = (tid & 15) * 4;
;     const int sn = tid >> 3, sk = (tid & 7) * 8;
;     int tile = blockIdx.x;
;     f32x4 v0 = {0.f, 0.f, 0.f, 0.f}, v1 = {0.f, 0.f, 0.f, 0.f};
;     if (tile < ntile) { const int tn = tile % tilesN, tk = tile / tilesN; const float* s = src + (size_t)(tk * 64 + lr) * ldsrc + col0 + tn * 64 + lc;
;         v0 = __builtin_nontemporal_load((const f32x4*)s); v1 = __builtin_nontemporal_load((const f32x4*)(s + (size_t)32 * ldsrc)); }
;     for (; tile < ntile; tile += gridDim.x) {
;         const int tn = tile % tilesN, tk = tile / tilesN;
; #pragma unroll
;         for (int j = 0; j < 4; ++j) { T[lr * 65 + lc + j] = v0[j]; T[(lr + 32) * 65 + lc + j] = v1[j]; }
;         asm volatile("s_waitcnt lgkmcnt(0)" ::: "memory"); __builtin_amdgcn_s_barrier(); asm volatile("" ::: "memory");
;         const int nx = tile + gridDim.x;
;         if (nx < ntile) { const int tn2 = nx % tilesN, tk2 = nx / tilesN; const float* s = src + (size_t)(tk2 * 64 + lr) * ldsrc + col0 + tn2 * 64 + lc;
;             v0 = __builtin_nontemporal_load((const f32x4*)s); v1 = __builtin_nontemporal_load((const f32x4*)(s + (size_t)32 * ldsrc)); }
;         float f[8];
; #pragma unroll
;         for (int j = 0; j < 8; ++j) f[j] = T[(sk + j) * 65 + sn];
;         *(u32x4*)(dst + (size_t)(tn * 64 + sn) * ldd + tk * 64 + sk) = pack8(f);
;         asm volatile("s_waitcnt lgkmcnt(0)" ::: "memory"); __builtin_amdgcn_s_barrier(); asm volatile("" ::: "memory");
;     }
;     __syncthreads();
; }
; __device__ void prep_extras(const Params& p) {
;     const int gt = blockIdx.x * 512 + threadIdx.x, nt = gridDim.x * 512;
;     u16* W = (u16*)(p.ws + OFF_W1) + (size_t)12288 * 2048;
;     for (int e = gt; e < 512 * 2048; e += nt) { const int k = e & 2047, n = e >> 11; float v = 0.f;
;         if (n < 96) v = (1.f - p.in[26][k]) * p.in[29][k * 96 + n];
;         else if (n < 192) v = p.in[26][k] * p.in[29][k * 96 + n - 96];
;         else if (n < 288) v = (1.f - p.in[27][k]) * p.in[32][k * 96 + n - 192];
;         else if (n < 384) v = p.in[27][k] * p.in[32][k * 96 + n - 288];
;         W[e] = f2bf(v); }
; }
TCV4_noloadX:
	ds_read2_b32 v[156:157], v149 offset1:65
	ds_read2_b32 v[158:159], v149 offset0:130 offset1:195
	ds_read2_b32 v[160:161], v150 offset0:4 offset1:69
	ds_read2_b32 v[162:163], v150 offset0:134 offset1:199
	ds_read2_b32 v[164:165], v151 offset1:65
	ds_read2_b32 v[166:167], v151 offset0:130 offset1:195
	ds_read2_b32 v[168:169], v152 offset0:4 offset1:69
	ds_read2_b32 v[170:171], v152 offset0:134 offset1:199
	v_add_u32_e32 v154, s50, v144
	v_add_u32_e32 v155, s51, v144
	s_waitcnt lgkmcnt(7)
	v_cvt_pk_bf16_f32 v156, v156, v157
	s_waitcnt lgkmcnt(6)
	v_cvt_pk_bf16_f32 v157, v158, v159
	s_waitcnt lgkmcnt(5)
	v_cvt_pk_bf16_f32 v158, v160, v161
	s_waitcnt lgkmcnt(4)
	v_cvt_pk_bf16_f32 v159, v162, v163
	global_store_dwordx4 v154, v[156:159], s[44:45]
	s_waitcnt lgkmcnt(3)
	v_cvt_pk_bf16_f32 v164, v164, v165
	s_waitcnt lgkmcnt(2)
	v_cvt_pk_bf16_f32 v165, v166, v167
	s_waitcnt lgkmcnt(1)
	v_cvt_pk_bf16_f32 v166, v168, v169
	s_waitcnt lgkmcnt(0)
	v_cvt_pk_bf16_f32 v167, v170, v171
	global_store_dwordx4 v155, v[164:167], s[44:45]
	s_add_i32 s46, s46, s54
	s_cmpk_lt_i32 s46, 0x800
	s_cbranch_scc0 TCV4_exit
	s_cmpk_lt_i32 s55, 0x800
	s_cbranch_scc1 TCV4_w6X
	s_waitcnt vmcnt(2)
TCV4_w6X:
	s_waitcnt vmcnt(6)
TCV4_bodyY:
	ds_write2_b32 v173, v104, v105 offset1:1
	ds_write2_b32 v173, v106, v107 offset0:2 offset1:3
	ds_write2_b32 v174, v108, v109 offset1:1
	ds_write2_b32 v174, v110, v111 offset0:2 offset1:3
	ds_write2_b32 v175, v112, v113 offset1:1
	ds_write2_b32 v175, v114, v115 offset0:2 offset1:3
	ds_write2_b32 v176, v116, v117 offset1:1
	ds_write2_b32 v176, v118, v119 offset0:2 offset1:3
	s_add_i32 s47, s46, s62
	s_cmpk_lt_i32 s47, 0x800
	s_cselect_b32 s47, s47, s46
	s_and_b32 s52, s46, 0x3f
	s_lshr_b32 s53, s46, 6
	s_lshl_b32 s52, s52, 18
	s_lshl_b32 s53, s53, 7
	s_add_i32 s50, s52, s53
	s_and_b32 s52, s47, 0x3f
	s_lshr_b32 s53, s47, 6
	s_lshl_b32 s52, s52, 18
	s_lshl_b32 s53, s53, 7
	s_add_i32 s51, s52, s53
	s_waitcnt lgkmcnt(0)
	s_barrier
	s_add_i32 s55, s46, s54
	s_add_i32 s55, s55, s54
	s_cmpk_lt_i32 s55, 0x800
	s_cbranch_scc0 TCV4_noloadY
	s_add_i32 s47, s55, s62
	s_cmpk_lt_i32 s47, 0x800
	s_cselect_b32 s47, s47, s55
	s_and_b32 s52, s55, 0x3f
	s_lshr_b32 s53, s55, 6
	s_lshl_b32 s52, s52, 8
	s_lshl_b32 s53, s53, 22
	s_add_i32 s48, s52, s53
	s_and_b32 s52, s47, 0x3f
	s_lshr_b32 s53, s47, 6
	s_lshl_b32 s52, s52, 8
	s_lshl_b32 s53, s53, 22
	s_add_i32 s49, s52, s53
	v_add_u32_e32 v153, s48, v143
	v_add_u32_e32 v172, s49, v143
	global_load_dwordx4 v[104:107], v153, s[40:41] nt
	global_load_dwordx4 v[108:111], v153, s[42:43] nt
	global_load_dwordx4 v[112:115], v172, s[40:41] nt
	global_load_dwordx4 v[116:119], v172, s[42:43] nt
TCV4_noloadY:
	ds_read2_b32 v[156:157], v177 offset1:65
	ds_read2_b32 v[158:159], v177 offset0:130 offset1:195
	ds_read2_b32 v[160:161], v178 offset0:4 offset1:69
	ds_read2_b32 v[162:163], v178 offset0:134 offset1:199
	ds_read2_b32 v[164:165], v120 offset1:65
	ds_read2_b32 v[166:167], v120 offset0:130 offset1:195
	ds_read2_b32 v[168:169], v121 offset0:4 offset1:69
	ds_read2_b32 v[170:171], v121 offset0:134 offset1:199
	v_add_u32_e32 v154, s50, v144
	v_add_u32_e32 v155, s51, v144
	s_waitcnt lgkmcnt(7)
	v_cvt_pk_bf16_f32 v156, v156, v157
	s_waitcnt lgkmcnt(6)
	v_cvt_pk_bf16_f32 v157, v158, v159
	s_waitcnt lgkmcnt(5)
	v_cvt_pk_bf16_f32 v158, v160, v161
	s_waitcnt lgkmcnt(4)
	v_cvt_pk_bf16_f32 v159, v162, v163
	global_store_dwordx4 v154, v[156:159], s[44:45]
	s_waitcnt lgkmcnt(3)
	v_cvt_pk_bf16_f32 v164, v164, v165
	s_waitcnt lgkmcnt(2)
	v_cvt_pk_bf16_f32 v165, v166, v167
	s_waitcnt lgkmcnt(1)
	v_cvt_pk_bf16_f32 v166, v168, v169
	s_waitcnt lgkmcnt(0)
	v_cvt_pk_bf16_f32 v167, v170, v171
	global_store_dwordx4 v155, v[164:167], s[44:45]
	s_add_i32 s46, s46, s54
	s_cmpk_lt_i32 s46, 0x800
	s_cbranch_scc0 TCV4_exit
	s_cmpk_lt_i32 s55, 0x800
	s_cbranch_scc1 TCV4_w6Y
	s_waitcnt vmcnt(2)
TCV4_w6Y:
	s_waitcnt vmcnt(6)
	s_branch TCV4_bodyX
TCV4_exit:
.LBB0_681:
	s_waitcnt vmcnt(2)
	v_lshl_add_u32 v2, s70, 9, v1
	s_mov_b32 s2, 0x100000
	v_cmp_gt_i32_e32 vcc, s2, v2
	s_barrier
	s_and_saveexec_b64 s[2:3], vcc
	s_cbranch_execz .LBB0_698
	s_lshl_b32 s4, s62, 9
	v_ashrrev_i32_e32 v3, 31, v2
	v_lshl_add_u64 v[4:5], v[2:3], 1, s[64:65]
	s_mov_b64 s[6:7], 0x1f000000
	s_ashr_i32 s5, s4, 31
	v_lshl_add_u64 v[4:5], v[4:5], 0, s[6:7]
	s_lshl_b64 s[6:7], s[4:5], 1
	s_mov_b64 s[8:9], 0
	s_movk_i32 s5, 0x5f
	s_movk_i32 s18, 0xbf
	s_movk_i32 s19, 0x11f
	s_movk_i32 s20, 0x180
	s_movk_i32 s21, 0x60
	s_waitcnt vmcnt(1)
	v_mov_b32_e32 v7, 0
	s_mov_b32 s22, 0xfffff
	s_branch .LBB0_684

; __device__ __forceinline__ u32x4 pack8(const float* f) { u32x4 w; w.x = pk2(f[0], f[1]); w.y = pk2(f[2], f[3]); w.z = pk2(f[4], f[5]); w.w = pk2(f[6], f[7]); return w; }
; __device__ void tconv(unsigned char* smem, const float* src, int ldsrc, int col0, int N, int K, u16* dst, int ldd) {
;     float* T = (float*)smem;
;     const int tid = threadIdx.x, tilesN = N >> 6, ntile = tilesN * (K >> 6);
;     const int lr = tid >> 4, lc = (tid & 15) * 4;
;     const int sn = tid >> 3, sk = (tid & 7) * 8;
;     int tile = blockIdx.x;
;     f32x4 v0 = {0.f, 0.f, 0.f, 0.f}, v1 = {0.f, 0.f, 0.f, 0.f};
;     if (tile < ntile) { const int tn = tile % tilesN, tk = tile / tilesN; const float* s = src + (size_t)(tk * 64 + lr) * ldsrc + col0 + tn * 64 + lc;
;         v0 = __builtin_nontemporal_load((const f32x4*)s); v1 = __builtin_nontemporal_load((const f32x4*)(s + (size_t)32 * ldsrc)); }
;     for (; tile < ntile; tile += gridDim.x) {
;         const int tn = tile % tilesN, tk = tile / tilesN;
; #pragma unroll
;         for (int j = 0; j < 4; ++j) { T[lr * 65 + lc + j] = v0[j]; T[(lr + 32) * 65 + lc + j] = v1[j]; }
;         asm volatile("s_waitcnt lgkmcnt(0)" ::: "memory"); __builtin_amdgcn_s_barrier(); asm volatile("" ::: "memory");
;         const int nx = tile + gridDim.x;
;         if (nx < ntile) { const int tn2 = nx % tilesN, tk2 = nx / tilesN; const float* s = src + (size_t)(tk2 * 64 + lr) * ldsrc + col0 + tn2 * 64 + lc;
;             v0 = __builtin_nontemporal_load((const f32x4*)s); v1 = __builtin_nontemporal_load((const f32x4*)(s + (size_t)32 * ldsrc)); }
;         float f[8];
; #pragma unroll
;         for (int j = 0; j < 8; ++j) f[j] = T[(sk + j) * 65 + sn];
;         *(u32x4*)(dst + (size_t)(tn * 64 + sn) * ldd + tk * 64 + sk) = pack8(f);
;         asm volatile("s_waitcnt lgkmcnt(0)" ::: "memory"); __builtin_amdgcn_s_barrier(); asm volatile("" ::: "memory");
;     }
;     __syncthreads();
; }
; __global__ void __launch_bounds__(512, 2) mega(Params p) {
;     ...
;         tconv(smem, p.in[24], 16384, 12288, 4096, 2048, (u16*)(ws + OFF_W1Z), 2048); if ((REP_MASK >> 4) & 1) { tconv(smem, p.in[24], 16384, 12288, 4096, 2048, (u16*)(ws + OFF_W1Z), 2048); }
.LBB0_1013:
	s_cmpk_lt_i32 s70, 0x800
	v_lshrrev_b32_e32 v1, 4, v103
	s_cselect_b64 s[0:1], -1, 0
	s_cmpk_gt_i32 s70, 0x7ff
	v_lshrrev_b32_e32 v14, 3, v103
	s_cbranch_scc1 .LBB0_1020
	s_waitcnt vmcnt(0) lgkmcnt(0)
	s_barrier
	v_readlane_b32 s40, v251, 28
	v_readlane_b32 s41, v251, 29
	v_and_b32_e32 v142, 0x3ff, v0
	v_lshrrev_b32_e32 v153, 4, v142
	v_and_b32_e32 v154, 15, v142
	v_lshlrev_b32_e32 v154, 4, v154
	v_lshlrev_b32_e32 v143, 16, v153
	v_add_u32_e32 v143, v143, v154
	v_mul_u32_u24_e32 v145, 0x104, v153
	v_add_u32_e32 v145, v145, v154
	v_add_u32_e32 v146, 0x2080, v145
	v_add_u32_e32 v147, 0x4100, v145
	v_add_u32_e32 v148, 0x6180, v145
	v_lshrrev_b32_e32 v153, 3, v142
	v_and_b32_e32 v154, 7, v142
	v_mul_u32_u24_e32 v149, 0x820, v154
	v_lshl_add_u32 v149, v153, 2, v149
	v_add_u32_e32 v150, 0x400, v149
	v_add_u32_e32 v151, 0x4100, v149
	v_add_u32_e32 v152, 0x4500, v149
	v_add_u32_e32 v173, 0x8200, v145
	v_add_u32_e32 v174, 0x8200, v146
	v_add_u32_e32 v175, 0x8200, v147
	v_add_u32_e32 v176, 0x8200, v148
	v_add_u32_e32 v177, 0x8200, v149
	v_add_u32_e32 v178, 0x8200, v150
	v_add_u32_e32 v120, 0x8200, v151
	v_add_u32_e32 v121, 0x8200, v152
	v_lshlrev_b32_e32 v144, 12, v153
	v_lshl_add_u32 v144, v154, 4, v144
	s_add_u32 s44, s64, 0x1c000000
	s_addc_u32 s45, s65, 0
	s_lshl_b32 s54, s62, 1
	s_mov_b32 s46, s70
	s_waitcnt lgkmcnt(0)
	s_add_u32 s40, s40, 0xc000
	s_addc_u32 s41, s41, 0
	s_add_u32 s42, s40, 0x200000
	s_addc_u32 s43, s41, 0
	s_add_i32 s47, s46, s62
	s_cmpk_lt_i32 s47, 0x800
	s_cselect_b32 s47, s47, s46
	s_and_b32 s52, s46, 0x3f
	s_lshr_b32 s53, s46, 6
	s_lshl_b32 s52, s52, 8
	s_lshl_b32 s53, s53, 22
	s_add_i32 s48, s52, s53
	s_and_b32 s52, s47, 0x3f
	s_lshr_b32 s53, s47, 6
	s_lshl_b32 s52, s52, 8
	s_lshl_b32 s53, s53, 22
	s_add_i32 s49, s52, s53
	v_add_u32_e32 v153, s48, v143
	v_add_u32_e32 v172, s49, v143
	global_load_dwordx4 v[70:73], v153, s[40:41] nt
	global_load_dwordx4 v[74:77], v153, s[42:43] nt
	global_load_dwordx4 v[78:81], v172, s[40:41] nt
	global_load_dwordx4 v[82:85], v172, s[42:43] nt
	s_add_i32 s55, s46, s54
	s_cmpk_lt_i32 s55, 0x800
	s_cbranch_scc0 TCV5_pro1
	s_add_i32 s47, s55, s62
	s_cmpk_lt_i32 s47, 0x800
	s_cselect_b32 s47, s47, s55
	s_and_b32 s52, s55, 0x3f
	s_lshr_b32 s53, s55, 6
	s_lshl_b32 s52, s52, 8
	s_lshl_b32 s53, s53, 22
	s_add_i32 s48, s52, s53
	s_and_b32 s52, s47, 0x3f
	s_lshr_b32 s53, s47, 6
	s_lshl_b32 s52, s52, 8
	s_lshl_b32 s53, s53, 22
	s_add_i32 s49, s52, s53
	v_add_u32_e32 v153, s48, v143
	v_add_u32_e32 v172, s49, v143
	global_load_dwordx4 v[104:107], v153, s[40:41] nt
	global_load_dwordx4 v[108:111], v153, s[42:43] nt
	global_load_dwordx4 v[112:115], v172, s[40:41] nt
	global_load_dwordx4 v[116:119], v172, s[42:43] nt
	s_waitcnt vmcnt(4)
	s_branch TCV5_bodyX
TCV5_pro1:
	s_waitcnt vmcnt(0)
TCV5_bodyX:
	ds_write2_b32 v145, v70, v71 offset1:1
	ds_write2_b32 v145, v72, v73 offset0:2 offset1:3
	ds_write2_b32 v146, v74, v75 offset1:1
	ds_write2_b32 v146, v76, v77 offset0:2 offset1:3
	ds_write2_b32 v147, v78, v79 offset1:1
	ds_write2_b32 v147, v80, v81 offset0:2 offset1:3
	ds_write2_b32 v148, v82, v83 offset1:1
	ds_write2_b32 v148, v84, v85 offset0:2 offset1:3
	s_add_i32 s47, s46, s62
	s_cmpk_lt_i32 s47, 0x800
	s_cselect_b32 s47, s47, s46
	s_and_b32 s52, s46, 0x3f
	s_lshr_b32 s53, s46, 6
	s_lshl_b32 s52, s52, 18
	s_lshl_b32 s53, s53, 7
	s_add_i32 s50, s52, s53
	s_and_b32 s52, s47, 0x3f
	s_lshr_b32 s53, s47, 6
	s_lshl_b32 s52, s52, 18
	s_lshl_b32 s53, s53, 7
	s_add_i32 s51, s52, s53
	s_waitcnt lgkmcnt(0)
	s_barrier
	s_add_i32 s55, s46, s54
	s_add_i32 s55, s55, s54
	s_cmpk_lt_i32 s55, 0x800
	s_cbranch_scc0 TCV5_noloadX
	s_add_i32 s47, s55, s62
	s_cmpk_lt_i32 s47, 0x800
	s_cselect_b32 s47, s47, s55
	s_and_b32 s52, s55, 0x3f
	s_lshr_b32 s53, s55, 6
	s_lshl_b32 s52, s52, 8
	s_lshl_b32 s53, s53, 22
	s_add_i32 s48, s52, s53
	s_and_b32 s52, s47, 0x3f
	s_lshr_b32 s53, s47, 6
	s_lshl_b32 s52, s52, 8
	s_lshl_b32 s53, s53, 22
	s_add_i32 s49, s52, s53
	v_add_u32_e32 v153, s48, v143
	v_add_u32_e32 v172, s49, v143
	global_load_dwordx4 v[70:73], v153, s[40:41] nt
	global_load_dwordx4 v[74:77], v153, s[42:43] nt
	global_load_dwordx4 v[78:81], v172, s[40:41] nt
	global_load_dwordx4 v[82:85], v172, s[42:43] nt
TCV5_noloadX:
	ds_read2_b32 v[156:157], v149 offset1:65
	ds_read2_b32 v[158:159], v149 offset0:130 offset1:195
	ds_read2_b32 v[160:161], v150 offset0:4 offset1:69
	ds_read2_b32 v[162:163], v150 offset0:134 offset1:199
	ds_read2_b32 v[164:165], v151 offset1:65
	ds_read2_b32 v[166:167], v151 offset0:130 offset1:195
	ds_read2_b32 v[168:169], v152 offset0:4 offset1:69
	ds_read2_b32 v[170:171], v152 offset0:134 offset1:199
	v_add_u32_e32 v154, s50, v144
	v_add_u32_e32 v155, s51, v144
	s_waitcnt lgkmcnt(7)
	v_cvt_pk_bf16_f32 v156, v156, v157
	s_waitcnt lgkmcnt(6)
	v_cvt_pk_bf16_f32 v157, v158, v159
	s_waitcnt lgkmcnt(5)
	v_cvt_pk_bf16_f32 v158, v160, v161
	s_waitcnt lgkmcnt(4)
	v_cvt_pk_bf16_f32 v159, v162, v163
	global_store_dwordx4 v154, v[156:159], s[44:45]
	s_waitcnt lgkmcnt(3)
	v_cvt_pk_bf16_f32 v164, v164, v165
	s_waitcnt lgkmcnt(2)
	v_cvt_pk_bf16_f32 v165, v166, v167
	s_waitcnt lgkmcnt(1)
	v_cvt_pk_bf16_f32 v166, v168, v169
	s_waitcnt lgkmcnt(0)
	v_cvt_pk_bf16_f32 v167, v170, v171
	global_store_dwordx4 v155, v[164:167], s[44:45]
	s_add_i32 s46, s46, s54
	s_cmpk_lt_i32 s46, 0x800
	s_cbranch_scc0 TCV5_exit
	s_cmpk_lt_i32 s55, 0x800
	s_cbranch_scc1 TCV5_w6X
	s_waitcnt vmcnt(2)
TCV5_w6X:
	s_waitcnt vmcnt(6)
; __device__ __forceinline__ u32x4 pack8(const float* f) { u32x4 w; w.x = pk2(f[0], f[1]); w.y = pk2(f[2], f[3]); w.z = pk2(f[4], f[5]); w.w = pk2(f[6], f[7]); return w; }
; __device__ void tconv(unsigned char* smem, const float* src, int ldsrc, int col0, int N, int K, u16* dst, int ldd) {
;     float* T = (float*)smem;
;     const int tid = threadIdx.x, tilesN = N >> 6, ntile = tilesN * (K >> 6);
;     const int lr = tid >> 4, lc = (tid & 15) * 4;
;     const int sn = tid >> 3, sk = (tid & 7) * 8;
;     int tile = blockIdx.x;
;     f32x4 v0 = {0.f, 0.f, 0.f, 0.f}, v1 = {0.f, 0.f, 0.f, 0.f};
;     if (tile < ntile) { const int tn = tile % tilesN, tk = tile / tilesN; const float* s = src + (size_t)(tk * 64 + lr) * ldsrc + col0 + tn * 64 + lc;
;         v0 = __builtin_nontemporal_load((const f32x4*)s); v1 = __builtin_nontemporal_load((const f32x4*)(s + (size_t)32 * ldsrc)); }
;     for (; tile < ntile; tile += gridDim.x) {
;         const int tn = tile % tilesN, tk = tile / tilesN;
; #pragma unroll
;         for (int j = 0; j < 4; ++j) { T[lr * 65 + lc + j] = v0[j]; T[(lr + 32) * 65 + lc + j] = v1[j]; }
;         asm volatile("s_waitcnt lgkmcnt(0)" ::: "memory"); __builtin_amdgcn_s_barrier(); asm volatile("" ::: "memory");
;         const int nx = tile + gridDim.x;
;         if (nx < ntile) { const int tn2 = nx % tilesN, tk2 = nx / tilesN; const float* s = src + (size_t)(tk2 * 64 + lr) * ldsrc + col0 + tn2 * 64 + lc;
;             v0 = __builtin_nontemporal_load((const f32x4*)s); v1 = __builtin_nontemporal_load((const f32x4*)(s + (size_t)32 * ldsrc)); }
;         float f[8];
; #pragma unroll
;         for (int j = 0; j < 8; ++j) f[j] = T[(sk + j) * 65 + sn];
;         *(u32x4*)(dst + (size_t)(tn * 64 + sn) * ldd + tk * 64 + sk) = pack8(f);
;         asm volatile("s_waitcnt lgkmcnt(0)" ::: "memory"); __builtin_amdgcn_s_barrier(); asm volatile("" ::: "memory");
;     }
;     __syncthreads();
; }
; __global__ void __launch_bounds__(512, 2) mega(Params p) {
;     ...
;         tconv(smem, p.in[39], 2048, 0, 2048, 4096, (u16*)(ws + OFF_W1OUT), 4096); if ((REP_MASK >> 4) & 1) { tconv(smem, p.in[39], 2048, 0, 2048, 4096, (u16*)(ws + OFF_W1OUT), 4096); }
TCV5_bodyY:
	ds_write2_b32 v173, v104, v105 offset1:1
	ds_write2_b32 v173, v106, v107 offset0:2 offset1:3
	ds_write2_b32 v174, v108, v109 offset1:1
	ds_write2_b32 v174, v110, v111 offset0:2 offset1:3
	ds_write2_b32 v175, v112, v113 offset1:1
	ds_write2_b32 v175, v114, v115 offset0:2 offset1:3
	ds_write2_b32 v176, v116, v117 offset1:1
	ds_write2_b32 v176, v118, v119 offset0:2 offset1:3
	s_add_i32 s47, s46, s62
	s_cmpk_lt_i32 s47, 0x800
	s_cselect_b32 s47, s47, s46
	s_and_b32 s52, s46, 0x3f
	s_lshr_b32 s53, s46, 6
	s_lshl_b32 s52, s52, 18
	s_lshl_b32 s53, s53, 7
	s_add_i32 s50, s52, s53
	s_and_b32 s52, s47, 0x3f
	s_lshr_b32 s53, s47, 6
	s_lshl_b32 s52, s52, 18
	s_lshl_b32 s53, s53, 7
	s_add_i32 s51, s52, s53
	s_waitcnt lgkmcnt(0)
	s_barrier
	s_add_i32 s55, s46, s54
	s_add_i32 s55, s55, s54
	s_cmpk_lt_i32 s55, 0x800
	s_cbranch_scc0 TCV5_noloadY
	s_add_i32 s47, s55, s62
	s_cmpk_lt_i32 s47, 0x800
	s_cselect_b32 s47, s47, s55
	s_and_b32 s52, s55, 0x3f
	s_lshr_b32 s53, s55, 6
	s_lshl_b32 s52, s52, 8
	s_lshl_b32 s53, s53, 22
	s_add_i32 s48, s52, s53
	s_and_b32 s52, s47, 0x3f
	s_lshr_b32 s53, s47, 6
	s_lshl_b32 s52, s52, 8
	s_lshl_b32 s53, s53, 22
	s_add_i32 s49, s52, s53
	v_add_u32_e32 v153, s48, v143
	v_add_u32_e32 v172, s49, v143
	global_load_dwordx4 v[104:107], v153, s[40:41] nt
	global_load_dwordx4 v[108:111], v153, s[42:43] nt
	global_load_dwordx4 v[112:115], v172, s[40:41] nt
	global_load_dwordx4 v[116:119], v172, s[42:43] nt
TCV5_noloadY:
	ds_read2_b32 v[156:157], v177 offset1:65
	ds_read2_b32 v[158:159], v177 offset0:130 offset1:195
	ds_read2_b32 v[160:161], v178 offset0:4 offset1:69
	ds_read2_b32 v[162:163], v178 offset0:134 offset1:199
	ds_read2_b32 v[164:165], v120 offset1:65
	ds_read2_b32 v[166:167], v120 offset0:130 offset1:195
	ds_read2_b32 v[168:169], v121 offset0:4 offset1:69
	ds_read2_b32 v[170:171], v121 offset0:134 offset1:199
	v_add_u32_e32 v154, s50, v144
	v_add_u32_e32 v155, s51, v144
	s_waitcnt lgkmcnt(7)
	v_cvt_pk_bf16_f32 v156, v156, v157
	s_waitcnt lgkmcnt(6)
	v_cvt_pk_bf16_f32 v157, v158, v159
	s_waitcnt lgkmcnt(5)
	v_cvt_pk_bf16_f32 v158, v160, v161
	s_waitcnt lgkmcnt(4)
	v_cvt_pk_bf16_f32 v159, v162, v163
	global_store_dwordx4 v154, v[156:159], s[44:45]
	s_waitcnt lgkmcnt(3)
	v_cvt_pk_bf16_f32 v164, v164, v165
	s_waitcnt lgkmcnt(2)
	v_cvt_pk_bf16_f32 v165, v166, v167
	s_waitcnt lgkmcnt(1)
	v_cvt_pk_bf16_f32 v166, v168, v169
	s_waitcnt lgkmcnt(0)
	v_cvt_pk_bf16_f32 v167, v170, v171
	global_store_dwordx4 v155, v[164:167], s[44:45]
	s_add_i32 s46, s46, s54
	s_cmpk_lt_i32 s46, 0x800
	s_cbranch_scc0 TCV5_exit
	s_cmpk_lt_i32 s55, 0x800
	s_cbranch_scc1 TCV5_w6Y
	s_waitcnt vmcnt(2)
TCV5_w6Y:
	s_waitcnt vmcnt(6)
	s_branch TCV5_bodyX
TCV5_exit:
.LBB0_1020:
	s_andn2_b64 vcc, exec, s[0:1]
	s_barrier
	s_cbranch_vccnz .LBB0_1027
	s_waitcnt vmcnt(0) lgkmcnt(0)
	s_barrier
	v_readlane_b32 s40, v250, 15
	v_readlane_b32 s41, v250, 16
	v_and_b32_e32 v142, 0x3ff, v0
	v_lshrrev_b32_e32 v153, 4, v142
	v_and_b32_e32 v154, 15, v142
	v_lshlrev_b32_e32 v154, 4, v154
	v_lshlrev_b32_e32 v143, 13, v153
	v_add_u32_e32 v143, v143, v154
	v_mul_u32_u24_e32 v145, 0x104, v153
	v_add_u32_e32 v145, v145, v154
	v_add_u32_e32 v146, 0x2080, v145
	v_add_u32_e32 v147, 0x4100, v145
	v_add_u32_e32 v148, 0x6180, v145
	v_lshrrev_b32_e32 v153, 3, v142
	v_and_b32_e32 v154, 7, v142
	v_mul_u32_u24_e32 v149, 0x820, v154
	v_lshl_add_u32 v149, v153, 2, v149
	v_add_u32_e32 v150, 0x400, v149
	v_add_u32_e32 v151, 0x4100, v149
	v_add_u32_e32 v152, 0x4500, v149
	v_add_u32_e32 v173, 0x8200, v145
	v_add_u32_e32 v174, 0x8200, v146
	v_add_u32_e32 v175, 0x8200, v147
	v_add_u32_e32 v176, 0x8200, v148
	v_add_u32_e32 v177, 0x8200, v149
	v_add_u32_e32 v178, 0x8200, v150
	v_add_u32_e32 v120, 0x8200, v151
	v_add_u32_e32 v121, 0x8200, v152
	v_lshlrev_b32_e32 v144, 13, v153
	v_lshl_add_u32 v144, v154, 4, v144
	s_add_u32 s44, s64, 0x1d000000
	s_addc_u32 s45, s65, 0
	s_lshl_b32 s54, s62, 1
	s_mov_b32 s46, s70
	s_waitcnt lgkmcnt(0)
	s_add_u32 s42, s40, 0x40000
	s_addc_u32 s43, s41, 0
	s_add_i32 s47, s46, s62
	s_cmpk_lt_i32 s47, 0x800
	s_cselect_b32 s47, s47, s46
	s_and_b32 s52, s46, 0x1f
	s_lshr_b32 s53, s46, 5
	s_lshl_b32 s52, s52, 8
	s_lshl_b32 s53, s53, 19
	s_add_i32 s48, s52, s53
	s_and_b32 s52, s47, 0x1f
	s_lshr_b32 s53, s47, 5
	s_lshl_b32 s52, s52, 8
	s_lshl_b32 s53, s53, 19
	s_add_i32 s49, s52, s53
	v_add_u32_e32 v153, s48, v143
	v_add_u32_e32 v172, s49, v143
	global_load_dwordx4 v[70:73], v153, s[40:41] nt
	global_load_dwordx4 v[74:77], v153, s[42:43] nt
	global_load_dwordx4 v[78:81], v172, s[40:41] nt
	global_load_dwordx4 v[82:85], v172, s[42:43] nt
	s_add_i32 s55, s46, s54
	s_cmpk_lt_i32 s55, 0x800
	s_cbranch_scc0 TCV6_pro1
	s_add_i32 s47, s55, s62
	s_cmpk_lt_i32 s47, 0x800
	s_cselect_b32 s47, s47, s55
	s_and_b32 s52, s55, 0x1f
	s_lshr_b32 s53, s55, 5
	s_lshl_b32 s52, s52, 8
	s_lshl_b32 s53, s53, 19
	s_add_i32 s48, s52, s53
	s_and_b32 s52, s47, 0x1f
	s_lshr_b32 s53, s47, 5
	s_lshl_b32 s52, s52, 8
	s_lshl_b32 s53, s53, 19
	s_add_i32 s49, s52, s53
	v_add_u32_e32 v153, s48, v143
	v_add_u32_e32 v172, s49, v143
	global_load_dwordx4 v[104:107], v153, s[40:41] nt
	global_load_dwordx4 v[108:111], v153, s[42:43] nt
	global_load_dwordx4 v[112:115], v172, s[40:41] nt
	global_load_dwordx4 v[116:119], v172, s[42:43] nt
	s_waitcnt vmcnt(4)
	s_branch TCV6_bodyX
TCV6_pro1:
	s_waitcnt vmcnt(0)
; __device__ __forceinline__ u32x4 pack8(const float* f) { u32x4 w; w.x = pk2(f[0], f[1]); w.y = pk2(f[2], f[3]); w.z = pk2(f[4], f[5]); w.w = pk2(f[6], f[7]); return w; }
; __device__ void tconv(unsigned char* smem, const float* src, int ldsrc, int col0, int N, int K, u16* dst, int ldd) {
;     float* T = (float*)smem;
;     const int tid = threadIdx.x, tilesN = N >> 6, ntile = tilesN * (K >> 6);
;     const int lr = tid >> 4, lc = (tid & 15) * 4;
;     const int sn = tid >> 3, sk = (tid & 7) * 8;
;     int tile = blockIdx.x;
;     f32x4 v0 = {0.f, 0.f, 0.f, 0.f}, v1 = {0.f, 0.f, 0.f, 0.f};
;     if (tile < ntile) { const int tn = tile % tilesN, tk = tile / tilesN; const float* s = src + (size_t)(tk * 64 + lr) * ldsrc + col0 + tn * 64 + lc;
;         v0 = __builtin_nontemporal_load((const f32x4*)s); v1 = __builtin_nontemporal_load((const f32x4*)(s + (size_t)32 * ldsrc)); }
;     for (; tile < ntile; tile += gridDim.x) {
;         const int tn = tile % tilesN, tk = tile / tilesN;
; #pragma unroll
;         for (int j = 0; j < 4; ++j) { T[lr * 65 + lc + j] = v0[j]; T[(lr + 32) * 65 + lc + j] = v1[j]; }
;         asm volatile("s_waitcnt lgkmcnt(0)" ::: "memory"); __builtin_amdgcn_s_barrier(); asm volatile("" ::: "memory");
;         const int nx = tile + gridDim.x;
;         if (nx < ntile) { const int tn2 = nx % tilesN, tk2 = nx / tilesN; const float* s = src + (size_t)(tk2 * 64 + lr) * ldsrc + col0 + tn2 * 64 + lc;
;             v0 = __builtin_nontemporal_load((const f32x4*)s); v1 = __builtin_nontemporal_load((const f32x4*)(s + (size_t)32 * ldsrc)); }
;         float f[8];
; #pragma unroll
;         for (int j = 0; j < 8; ++j) f[j] = T[(sk + j) * 65 + sn];
;         *(u32x4*)(dst + (size_t)(tn * 64 + sn) * ldd + tk * 64 + sk) = pack8(f);
;         asm volatile("s_waitcnt lgkmcnt(0)" ::: "memory"); __builtin_amdgcn_s_barrier(); asm volatile("" ::: "memory");
;     }
;     __syncthreads();
; }
TCV6_bodyX:
	ds_write2_b32 v145, v70, v71 offset1:1
	ds_write2_b32 v145, v72, v73 offset0:2 offset1:3
	ds_write2_b32 v146, v74, v75 offset1:1
	ds_write2_b32 v146, v76, v77 offset0:2 offset1:3
	ds_write2_b32 v147, v78, v79 offset1:1
	ds_write2_b32 v147, v80, v81 offset0:2 offset1:3
	ds_write2_b32 v148, v82, v83 offset1:1
	ds_write2_b32 v148, v84, v85 offset0:2 offset1:3
	s_add_i32 s47, s46, s62
	s_cmpk_lt_i32 s47, 0x800
	s_cselect_b32 s47, s47, s46
	s_and_b32 s52, s46, 0x1f
	s_lshr_b32 s53, s46, 5
	s_lshl_b32 s52, s52, 19
	s_lshl_b32 s53, s53, 7
	s_add_i32 s50, s52, s53
	s_and_b32 s52, s47, 0x1f
	s_lshr_b32 s53, s47, 5
	s_lshl_b32 s52, s52, 19
	s_lshl_b32 s53, s53, 7
	s_add_i32 s51, s52, s53
	s_waitcnt lgkmcnt(0)
	s_barrier
	s_add_i32 s55, s46, s54
	s_add_i32 s55, s55, s54
	s_cmpk_lt_i32 s55, 0x800
	s_cbranch_scc0 TCV6_noloadX
	s_add_i32 s47, s55, s62
	s_cmpk_lt_i32 s47, 0x800
	s_cselect_b32 s47, s47, s55
	s_and_b32 s52, s55, 0x1f
	s_lshr_b32 s53, s55, 5
	s_lshl_b32 s52, s52, 8
	s_lshl_b32 s53, s53, 19
	s_add_i32 s48, s52, s53
	s_and_b32 s52, s47, 0x1f
	s_lshr_b32 s53, s47, 5
	s_lshl_b32 s52, s52, 8
	s_lshl_b32 s53, s53, 19
	s_add_i32 s49, s52, s53
	v_add_u32_e32 v153, s48, v143
	v_add_u32_e32 v172, s49, v143
	global_load_dwordx4 v[70:73], v153, s[40:41] nt
	global_load_dwordx4 v[74:77], v153, s[42:43] nt
	global_load_dwordx4 v[78:81], v172, s[40:41] nt
	global_load_dwordx4 v[82:85], v172, s[42:43] nt
TCV6_noloadX:
	ds_read2_b32 v[156:157], v149 offset1:65
	ds_read2_b32 v[158:159], v149 offset0:130 offset1:195
	ds_read2_b32 v[160:161], v150 offset0:4 offset1:69
	ds_read2_b32 v[162:163], v150 offset0:134 offset1:199
	ds_read2_b32 v[164:165], v151 offset1:65
	ds_read2_b32 v[166:167], v151 offset0:130 offset1:195
	ds_read2_b32 v[168:169], v152 offset0:4 offset1:69
	ds_read2_b32 v[170:171], v152 offset0:134 offset1:199
	v_add_u32_e32 v154, s50, v144
	v_add_u32_e32 v155, s51, v144
	s_waitcnt lgkmcnt(7)
	v_cvt_pk_bf16_f32 v156, v156, v157
	s_waitcnt lgkmcnt(6)
	v_cvt_pk_bf16_f32 v157, v158, v159
	s_waitcnt lgkmcnt(5)
	v_cvt_pk_bf16_f32 v158, v160, v161
	s_waitcnt lgkmcnt(4)
	v_cvt_pk_bf16_f32 v159, v162, v163
	global_store_dwordx4 v154, v[156:159], s[44:45]
	s_waitcnt lgkmcnt(3)
	v_cvt_pk_bf16_f32 v164, v164, v165
	s_waitcnt lgkmcnt(2)
	v_cvt_pk_bf16_f32 v165, v166, v167
	s_waitcnt lgkmcnt(1)
	v_cvt_pk_bf16_f32 v166, v168, v169
	s_waitcnt lgkmcnt(0)
	v_cvt_pk_bf16_f32 v167, v170, v171
	global_store_dwordx4 v155, v[164:167], s[44:45]
	s_add_i32 s46, s46, s54
	s_cmpk_lt_i32 s46, 0x800
	s_cbranch_scc0 TCV6_exit
	s_cmpk_lt_i32 s55, 0x800
	s_cbranch_scc1 TCV6_w6X
	s_waitcnt vmcnt(2)
TCV6_w6X:
	s_waitcnt vmcnt(6)
TCV6_bodyY:
	ds_write2_b32 v173, v104, v105 offset1:1
	ds_write2_b32 v173, v106, v107 offset0:2 offset1:3
	ds_write2_b32 v174, v108, v109 offset1:1
	ds_write2_b32 v174, v110, v111 offset0:2 offset1:3
	ds_write2_b32 v175, v112, v113 offset1:1
	ds_write2_b32 v175, v114, v115 offset0:2 offset1:3
	ds_write2_b32 v176, v116, v117 offset1:1
	ds_write2_b32 v176, v118, v119 offset0:2 offset1:3
	s_add_i32 s47, s46, s62
	s_cmpk_lt_i32 s47, 0x800
	s_cselect_b32 s47, s47, s46
	s_and_b32 s52, s46, 0x1f
	s_lshr_b32 s53, s46, 5
	s_lshl_b32 s52, s52, 19
	s_lshl_b32 s53, s53, 7
	s_add_i32 s50, s52, s53
	s_and_b32 s52, s47, 0x1f
	s_lshr_b32 s53, s47, 5
	s_lshl_b32 s52, s52, 19
	s_lshl_b32 s53, s53, 7
	s_add_i32 s51, s52, s53
	s_waitcnt lgkmcnt(0)
	s_barrier
	s_add_i32 s55, s46, s54
	s_add_i32 s55, s55, s54
	s_cmpk_lt_i32 s55, 0x800
	s_cbranch_scc0 TCV6_noloadY
	s_add_i32 s47, s55, s62
	s_cmpk_lt_i32 s47, 0x800
	s_cselect_b32 s47, s47, s55
	s_and_b32 s52, s55, 0x1f
	s_lshr_b32 s53, s55, 5
	s_lshl_b32 s52, s52, 8
	s_lshl_b32 s53, s53, 19
	s_add_i32 s48, s52, s53
	s_and_b32 s52, s47, 0x1f
	s_lshr_b32 s53, s47, 5
	s_lshl_b32 s52, s52, 8
	s_lshl_b32 s53, s53, 19
	s_add_i32 s49, s52, s53
	v_add_u32_e32 v153, s48, v143
	v_add_u32_e32 v172, s49, v143
	global_load_dwordx4 v[104:107], v153, s[40:41] nt
	global_load_dwordx4 v[108:111], v153, s[42:43] nt
	global_load_dwordx4 v[112:115], v172, s[40:41] nt
	global_load_dwordx4 v[116:119], v172, s[42:43] nt
TCV6_noloadY:
	ds_read2_b32 v[156:157], v177 offset1:65
	ds_read2_b32 v[158:159], v177 offset0:130 offset1:195
	ds_read2_b32 v[160:161], v178 offset0:4 offset1:69
	ds_read2_b32 v[162:163], v178 offset0:134 offset1:199
	ds_read2_b32 v[164:165], v120 offset1:65
	ds_read2_b32 v[166:167], v120 offset0:130 offset1:195
	ds_read2_b32 v[168:169], v121 offset0:4 offset1:69
	ds_read2_b32 v[170:171], v121 offset0:134 offset1:199
	v_add_u32_e32 v154, s50, v144
	v_add_u32_e32 v155, s51, v144
	s_waitcnt lgkmcnt(7)
	v_cvt_pk_bf16_f32 v156, v156, v157
	s_waitcnt lgkmcnt(6)
	v_cvt_pk_bf16_f32 v157, v158, v159
	s_waitcnt lgkmcnt(5)
	v_cvt_pk_bf16_f32 v158, v160, v161
	s_waitcnt lgkmcnt(4)
	v_cvt_pk_bf16_f32 v159, v162, v163
	global_store_dwordx4 v154, v[156:159], s[44:45]
	s_waitcnt lgkmcnt(3)
	v_cvt_pk_bf16_f32 v164, v164, v165
	s_waitcnt lgkmcnt(2)
	v_cvt_pk_bf16_f32 v165, v166, v167
	s_waitcnt lgkmcnt(1)
	v_cvt_pk_bf16_f32 v166, v168, v169
	s_waitcnt lgkmcnt(0)
	v_cvt_pk_bf16_f32 v167, v170, v171
	global_store_dwordx4 v155, v[164:167], s[44:45]
	s_add_i32 s46, s46, s54
	s_cmpk_lt_i32 s46, 0x800
	s_cbranch_scc0 TCV6_exit
	s_cmpk_lt_i32 s55, 0x800
	s_cbranch_scc1 TCV6_w6Y
	s_waitcnt vmcnt(2)
TCV6_w6Y:
	s_waitcnt vmcnt(6)
	s_branch TCV6_bodyX
TCV6_exit:
.LBB0_1027:
	s_barrier
